# hand-written GQA/SWA in-proj q/k/v epilogue: norm weights hoisted, rope tables double-buffered one row group ahead, no waits on stores
# speedup vs baseline: 1.0075x; 1.0075x over previous
.LBB0_424:
	s_cmp_eq_u32 s39, 4
	s_cbranch_scc1 .LBB0_979
	s_cmp_eq_u32 s39, 0
	s_cselect_b64 s[22:23], -1, 0
	s_cmp_gt_i32 s74, 2
	s_cselect_b64 s[4:5], -1, 0
	s_and_b64 s[4:5], s[22:23], s[4:5]
	v_mbcnt_lo_u32_b32 v187, -1, 0
	v_mbcnt_hi_u32_b32 v187, -1, v187
	s_and_b64 vcc, exec, s[4:5]
	v_and_b32_e32 v189, 15, v187
	v_ashrrev_i32_e32 v191, 4, v187
	s_cbranch_vccnz .LBB0_972
	s_cmp_eq_u32 s39, 3
	s_cselect_b64 s[4:5], -1, 0
	s_cmp_gt_i32 s74, 5
	s_cselect_b64 s[6:7], -1, 0
	s_and_b64 s[4:5], s[4:5], s[6:7]
	s_andn2_b64 vcc, exec, s[4:5]
	s_mov_b64 s[4:5], -1
	s_cbranch_vccz .LBB0_972
	s_cmp_lt_i32 s39, 2
	s_cbranch_scc1 .LBB0_687
	s_cmp_gt_i32 s39, 2
	s_cbranch_scc0 .LBB0_639
	s_load_dwordx2 s[4:5], s[0:1], 0xd0
	v_readlane_b32 s48, v254, 36
	v_readlane_b32 s49, v254, 45
	v_readlane_b32 s50, v255, 17
	v_readlane_b32 s96, v255, 32
	v_readlane_b32 s97, v255, 33
	v_lshlrev_b32_e32 v131, 7, v189
	v_lshl_add_u32 v131, v191, 4, v131
	v_add_u32_e32 v132, 0x20000, v131
	v_lshlrev_b32_e32 v133, 5, v191
	s_lshl_b32 s51, s48, 8
	s_add_u32 s51, s51, s49
	s_sub_u32 s58, s48, 32
	s_and_b32 s59, s58, 3
	s_lshl_b32 s59, s59, 8
	s_add_u32 s59, s59, s49
	s_cmp_gt_u32 s74, 3
	s_cbranch_scc1 .Lq3_kv
	s_lshl_b32 s35, s51, 11
	s_lshl_b32 s70, s74, 9
	s_add_u32 s35, s35, s70
	s_lshl_b32 s70, s19, 1
	s_add_u32 s35, s35, s70
	s_add_u32 s35, s35, 0x3c00000
	s_mov_b32 s33, 0x8000
	s_mov_b32 s34, 0x28000
	s_mov_b32 s36, 0x3e38aa3b
	s_mov_b32 s71, 0xa0
	v_lshlrev_b32_e32 v130, 11, v189
	s_mov_b64 s[24:25], 0
	s_branch .Lq3_common
.Lq3_kv:
	s_mov_b32 s35, s51
	s_cmp_lt_u32 s48, 32
	s_cbranch_scc1 .Lq3_kv_ctx
	s_lshr_b32 s35, s58, 2
	s_mul_i32 s35, s35, 0x600
	s_add_u32 s35, s35, 0x2200
	s_add_u32 s35, s35, s59
.Lq3_kv_ctx:
	s_lshl_b32 s35, s35, 9
	s_lshl_b32 s70, s19, 1
	s_add_u32 s35, s35, s70
	s_mov_b32 s70, 0xc900000
	s_cmp_eq_u32 s74, 4
	s_cselect_b32 s70, s70, 0xd700000
	s_add_u32 s35, s35, s70
	s_mov_b32 s33, 0x2000
	s_mov_b32 s34, 0xa000
	s_mov_b32 s36, 1.0
	s_mov_b32 s71, 0xa8
	v_lshlrev_b32_e32 v130, 9, v189
	s_mov_b64 s[24:25], s[96:97]
.Lq3_common:
	v_lshl_add_u32 v130, v191, 4, v130
	s_waitcnt lgkmcnt(0)
	s_add_u32 s6, s4, s35
	s_addc_u32 s7, s5, 0
	s_add_u32 s6, s6, s24
	s_addc_u32 s7, s7, s25
	s_lshl_b32 s59, s59, 7
	s_add_u32 s8, s4, s59
	s_addc_u32 s9, s5, 0
	s_add_u32 s8, s8, 0x180000
	s_addc_u32 s9, s9, 0
	s_cmp_eq_u32 s74, 5
	s_cbranch_scc1 .Lq3_D
	s_cmp_lg_u32 s50, 0
	s_cbranch_scc0 .Lq3_nonorm
	s_add_u32 s24, s0, s71
	s_addc_u32 s25, s1, 0
	s_load_dwordx2 s[24:25], s[24:25], 0x0
	s_cmp_lt_u32 s48, 32
	s_waitcnt lgkmcnt(0)
	s_cbranch_scc1 .Lq3_B
	s_branch .Lq3_A
.Lq3_nonorm:
	s_cmp_lt_u32 s48, 32
	s_cbranch_scc1 .Lq3_D
	s_branch .Lq3_C
.Lq3_A:
	global_load_dwordx4 v[148:151], v133, s[24:25]
	global_load_dwordx4 v[152:155], v133, s[24:25] offset:16
	global_load_dwordx4 v[156:159], v133, s[24:25] offset:128
	global_load_dwordx4 v[160:163], v133, s[24:25] offset:144
	global_load_dwordx4 v[164:167], v131, s[8:9]
	global_load_dwordx4 v[168:171], v132, s[8:9]
	global_load_dwordx4 v[172:175], v131, s[8:9] offset:64
	global_load_dwordx4 v[176:179], v132, s[8:9] offset:64
	s_add_u32 s8, s8, 0x800
	s_addc_u32 s9, s9, 0
	global_load_dwordx4 v[202:205], v131, s[8:9]
	global_load_dwordx4 v[206:209], v132, s[8:9]
	global_load_dwordx4 v[210:213], v131, s[8:9] offset:64
	global_load_dwordx4 v[214:217], v132, s[8:9] offset:64
	v_mul_f32_e32 v134, v127, v127
	v_fmac_f32_e32 v134, v126, v126
	v_fmac_f32_e32 v134, v128, v128
	v_fmac_f32_e32 v134, v129, v129
	v_fmac_f32_e32 v134, v122, v122
	v_fmac_f32_e32 v134, v123, v123
	v_fmac_f32_e32 v134, v124, v124
	v_fmac_f32_e32 v134, v125, v125
	v_fmac_f32_e32 v134, v118, v118
	v_fmac_f32_e32 v134, v119, v119
	v_pk_mul_f32 v[136:137], v[120:121], v[120:121]
	v_pk_mul_f32 v[138:139], v[114:115], v[114:115]
	v_add_f32_e32 v134, v136, v134
	v_add_f32_e32 v134, v137, v134
	v_add_f32_e32 v134, v138, v134
	v_pk_mul_f32 v[136:137], v[116:117], v[116:117]
	v_add_f32_e32 v134, v139, v134
	v_add_f32_e32 v134, v136, v134
	v_add_f32_e32 v134, v137, v134
	ds_swizzle_b32 v135, v134 offset:swizzle(SWAP,16)
	s_waitcnt lgkmcnt(0)
	v_add_f32_e32 v134, v134, v135
	v_mov_b32_e32 v135, v134
	s_nop 1
	v_permlane32_swap_b32 v134, v135
	s_nop 1
	v_add_f32_e32 v134, v134, v135
	v_fmamk_f32 v134, v134, 0x3c800000, v242
	v_rsq_f32_e32 v134, v134
	s_waitcnt vmcnt(8)
	v_pk_mul_f32 v[136:137], v[134:135], v[148:149] op_sel_hi:[0,1]
	v_pk_mul_f32 v[126:127], v[126:127], v[136:137]
	v_pk_mul_f32 v[136:137], v[134:135], v[150:151] op_sel_hi:[0,1]
	v_pk_mul_f32 v[128:129], v[128:129], v[136:137]
	v_pk_mul_f32 v[136:137], v[134:135], v[152:153] op_sel_hi:[0,1]
	v_pk_mul_f32 v[122:123], v[122:123], v[136:137]
	v_pk_mul_f32 v[136:137], v[134:135], v[154:155] op_sel_hi:[0,1]
	v_pk_mul_f32 v[124:125], v[124:125], v[136:137]
	v_pk_mul_f32 v[136:137], v[134:135], v[156:157] op_sel_hi:[0,1]
	v_pk_mul_f32 v[118:119], v[118:119], v[136:137]
	v_pk_mul_f32 v[136:137], v[134:135], v[158:159] op_sel_hi:[0,1]
	v_pk_mul_f32 v[120:121], v[120:121], v[136:137]
	v_pk_mul_f32 v[136:137], v[134:135], v[160:161] op_sel_hi:[0,1]
	v_pk_mul_f32 v[114:115], v[114:115], v[136:137]
	v_pk_mul_f32 v[136:137], v[134:135], v[162:163] op_sel_hi:[0,1]
	v_pk_mul_f32 v[116:117], v[116:117], v[136:137]
	s_waitcnt vmcnt(4)
	v_pk_mul_f32 v[136:137], v[126:127], v[168:169] op_sel:[1,0] op_sel_hi:[0,0]
	v_pk_fma_f32 v[126:127], v[126:127], v[164:165], v[136:137] op_sel:[0,0,0] op_sel_hi:[1,0,1] neg_lo:[0,0,1]
	v_pk_mul_f32 v[136:137], v[128:129], v[168:169] op_sel:[1,1] op_sel_hi:[0,1]
	v_pk_fma_f32 v[128:129], v[128:129], v[164:165], v[136:137] op_sel:[0,1,0] op_sel_hi:[1,1,1] neg_lo:[0,0,1]
	v_pk_mul_f32 v[136:137], v[122:123], v[170:171] op_sel:[1,0] op_sel_hi:[0,0]
	v_pk_fma_f32 v[122:123], v[122:123], v[166:167], v[136:137] op_sel:[0,0,0] op_sel_hi:[1,0,1] neg_lo:[0,0,1]
	v_pk_mul_f32 v[136:137], v[124:125], v[170:171] op_sel:[1,1] op_sel_hi:[0,1]
	v_pk_fma_f32 v[124:125], v[124:125], v[166:167], v[136:137] op_sel:[0,1,0] op_sel_hi:[1,1,1] neg_lo:[0,0,1]
	v_pk_mul_f32 v[126:127], v[126:127], s[36:37] op_sel_hi:[1,0]
	v_pk_mul_f32 v[128:129], v[128:129], s[36:37] op_sel_hi:[1,0]
	v_pk_mul_f32 v[122:123], v[122:123], s[36:37] op_sel_hi:[1,0]
	v_pk_mul_f32 v[124:125], v[124:125], s[36:37] op_sel_hi:[1,0]
	v_cvt_pk_bf16_f32 v140, v126, v127
	v_cvt_pk_bf16_f32 v141, v128, v129
	v_cvt_pk_bf16_f32 v142, v122, v123
	v_cvt_pk_bf16_f32 v143, v124, v125
	global_store_dwordx4 v130, v[140:143], s[6:7]
	v_pk_mul_f32 v[136:137], v[118:119], v[176:177] op_sel:[1,0] op_sel_hi:[0,0]
	v_pk_fma_f32 v[118:119], v[118:119], v[172:173], v[136:137] op_sel:[0,0,0] op_sel_hi:[1,0,1] neg_lo:[0,0,1]
	v_pk_mul_f32 v[136:137], v[120:121], v[176:177] op_sel:[1,1] op_sel_hi:[0,1]
	v_pk_fma_f32 v[120:121], v[120:121], v[172:173], v[136:137] op_sel:[0,1,0] op_sel_hi:[1,1,1] neg_lo:[0,0,1]
	v_pk_mul_f32 v[136:137], v[114:115], v[178:179] op_sel:[1,0] op_sel_hi:[0,0]
	v_pk_fma_f32 v[114:115], v[114:115], v[174:175], v[136:137] op_sel:[0,0,0] op_sel_hi:[1,0,1] neg_lo:[0,0,1]
	v_pk_mul_f32 v[136:137], v[116:117], v[178:179] op_sel:[1,1] op_sel_hi:[0,1]
	v_pk_fma_f32 v[116:117], v[116:117], v[174:175], v[136:137] op_sel:[0,1,0] op_sel_hi:[1,1,1] neg_lo:[0,0,1]
	v_pk_mul_f32 v[118:119], v[118:119], s[36:37] op_sel_hi:[1,0]
	v_pk_mul_f32 v[120:121], v[120:121], s[36:37] op_sel_hi:[1,0]
	v_pk_mul_f32 v[114:115], v[114:115], s[36:37] op_sel_hi:[1,0]
	v_pk_mul_f32 v[116:117], v[116:117], s[36:37] op_sel_hi:[1,0]
	v_cvt_pk_bf16_f32 v144, v118, v119
	v_cvt_pk_bf16_f32 v145, v120, v121
	v_cvt_pk_bf16_f32 v146, v114, v115
	v_cvt_pk_bf16_f32 v147, v116, v117
	global_store_dwordx4 v130, v[144:147], s[6:7] offset:64
	s_add_u32 s6, s6, s33
	s_addc_u32 s7, s7, 0
	s_add_u32 s8, s8, 0x800
	s_addc_u32 s9, s9, 0
	global_load_dwordx4 v[164:167], v131, s[8:9]
	global_load_dwordx4 v[168:171], v132, s[8:9]
	global_load_dwordx4 v[172:175], v131, s[8:9] offset:64
	global_load_dwordx4 v[176:179], v132, s[8:9] offset:64
	v_mul_f32_e32 v134, v109, v109
	v_fmac_f32_e32 v134, v108, v108
	v_fmac_f32_e32 v134, v110, v110
	v_fmac_f32_e32 v134, v111, v111
	v_fmac_f32_e32 v134, v104, v104
	v_fmac_f32_e32 v134, v105, v105
	v_fmac_f32_e32 v134, v106, v106
	v_fmac_f32_e32 v134, v107, v107
	v_fmac_f32_e32 v134, v100, v100
	v_fmac_f32_e32 v134, v101, v101
	v_pk_mul_f32 v[136:137], v[102:103], v[102:103]
	v_pk_mul_f32 v[138:139], v[96:97], v[96:97]
	v_add_f32_e32 v134, v136, v134
	v_add_f32_e32 v134, v137, v134
	v_add_f32_e32 v134, v138, v134
	v_pk_mul_f32 v[136:137], v[98:99], v[98:99]
	v_add_f32_e32 v134, v139, v134
	v_add_f32_e32 v134, v136, v134
	v_add_f32_e32 v134, v137, v134
	ds_swizzle_b32 v135, v134 offset:swizzle(SWAP,16)
	s_waitcnt lgkmcnt(0)
	v_add_f32_e32 v134, v134, v135
	v_mov_b32_e32 v135, v134
	s_nop 1
	v_permlane32_swap_b32 v134, v135
	s_nop 1
	v_add_f32_e32 v134, v134, v135
	v_fmamk_f32 v134, v134, 0x3c800000, v242
	v_rsq_f32_e32 v134, v134
	s_nop 0
	v_pk_mul_f32 v[136:137], v[134:135], v[148:149] op_sel_hi:[0,1]
	v_pk_mul_f32 v[108:109], v[108:109], v[136:137]
	v_pk_mul_f32 v[136:137], v[134:135], v[150:151] op_sel_hi:[0,1]
	v_pk_mul_f32 v[110:111], v[110:111], v[136:137]
	v_pk_mul_f32 v[136:137], v[134:135], v[152:153] op_sel_hi:[0,1]
	v_pk_mul_f32 v[104:105], v[104:105], v[136:137]
	v_pk_mul_f32 v[136:137], v[134:135], v[154:155] op_sel_hi:[0,1]
	v_pk_mul_f32 v[106:107], v[106:107], v[136:137]
	v_pk_mul_f32 v[136:137], v[134:135], v[156:157] op_sel_hi:[0,1]
	v_pk_mul_f32 v[100:101], v[100:101], v[136:137]
	v_pk_mul_f32 v[136:137], v[134:135], v[158:159] op_sel_hi:[0,1]
	v_pk_mul_f32 v[102:103], v[102:103], v[136:137]
	v_pk_mul_f32 v[136:137], v[134:135], v[160:161] op_sel_hi:[0,1]
	v_pk_mul_f32 v[96:97], v[96:97], v[136:137]
	v_pk_mul_f32 v[136:137], v[134:135], v[162:163] op_sel_hi:[0,1]
	v_pk_mul_f32 v[98:99], v[98:99], v[136:137]
	s_waitcnt vmcnt(6)
	v_pk_mul_f32 v[136:137], v[108:109], v[206:207] op_sel:[1,0] op_sel_hi:[0,0]
	v_pk_fma_f32 v[108:109], v[108:109], v[202:203], v[136:137] op_sel:[0,0,0] op_sel_hi:[1,0,1] neg_lo:[0,0,1]
	v_pk_mul_f32 v[136:137], v[110:111], v[206:207] op_sel:[1,1] op_sel_hi:[0,1]
	v_pk_fma_f32 v[110:111], v[110:111], v[202:203], v[136:137] op_sel:[0,1,0] op_sel_hi:[1,1,1] neg_lo:[0,0,1]
	v_pk_mul_f32 v[136:137], v[104:105], v[208:209] op_sel:[1,0] op_sel_hi:[0,0]
	v_pk_fma_f32 v[104:105], v[104:105], v[204:205], v[136:137] op_sel:[0,0,0] op_sel_hi:[1,0,1] neg_lo:[0,0,1]
	v_pk_mul_f32 v[136:137], v[106:107], v[208:209] op_sel:[1,1] op_sel_hi:[0,1]
	v_pk_fma_f32 v[106:107], v[106:107], v[204:205], v[136:137] op_sel:[0,1,0] op_sel_hi:[1,1,1] neg_lo:[0,0,1]
	v_pk_mul_f32 v[108:109], v[108:109], s[36:37] op_sel_hi:[1,0]
	v_pk_mul_f32 v[110:111], v[110:111], s[36:37] op_sel_hi:[1,0]
	v_pk_mul_f32 v[104:105], v[104:105], s[36:37] op_sel_hi:[1,0]
	v_pk_mul_f32 v[106:107], v[106:107], s[36:37] op_sel_hi:[1,0]
	v_cvt_pk_bf16_f32 v140, v108, v109
	v_cvt_pk_bf16_f32 v141, v110, v111
	v_cvt_pk_bf16_f32 v142, v104, v105
	v_cvt_pk_bf16_f32 v143, v106, v107
	global_store_dwordx4 v130, v[140:143], s[6:7]
	v_pk_mul_f32 v[136:137], v[100:101], v[214:215] op_sel:[1,0] op_sel_hi:[0,0]
	v_pk_fma_f32 v[100:101], v[100:101], v[210:211], v[136:137] op_sel:[0,0,0] op_sel_hi:[1,0,1] neg_lo:[0,0,1]
	v_pk_mul_f32 v[136:137], v[102:103], v[214:215] op_sel:[1,1] op_sel_hi:[0,1]
	v_pk_fma_f32 v[102:103], v[102:103], v[210:211], v[136:137] op_sel:[0,1,0] op_sel_hi:[1,1,1] neg_lo:[0,0,1]
	v_pk_mul_f32 v[136:137], v[96:97], v[216:217] op_sel:[1,0] op_sel_hi:[0,0]
	v_pk_fma_f32 v[96:97], v[96:97], v[212:213], v[136:137] op_sel:[0,0,0] op_sel_hi:[1,0,1] neg_lo:[0,0,1]
	v_pk_mul_f32 v[136:137], v[98:99], v[216:217] op_sel:[1,1] op_sel_hi:[0,1]
	v_pk_fma_f32 v[98:99], v[98:99], v[212:213], v[136:137] op_sel:[0,1,0] op_sel_hi:[1,1,1] neg_lo:[0,0,1]
	v_pk_mul_f32 v[100:101], v[100:101], s[36:37] op_sel_hi:[1,0]
	v_pk_mul_f32 v[102:103], v[102:103], s[36:37] op_sel_hi:[1,0]
	v_pk_mul_f32 v[96:97], v[96:97], s[36:37] op_sel_hi:[1,0]
	v_pk_mul_f32 v[98:99], v[98:99], s[36:37] op_sel_hi:[1,0]
	v_cvt_pk_bf16_f32 v144, v100, v101
	v_cvt_pk_bf16_f32 v145, v102, v103
	v_cvt_pk_bf16_f32 v146, v96, v97
	v_cvt_pk_bf16_f32 v147, v98, v99
	global_store_dwordx4 v130, v[144:147], s[6:7] offset:64
	s_add_u32 s6, s6, s33
	s_addc_u32 s7, s7, 0
	s_add_u32 s8, s8, 0x800
	s_addc_u32 s9, s9, 0
	global_load_dwordx4 v[202:205], v131, s[8:9]
	global_load_dwordx4 v[206:209], v132, s[8:9]
	global_load_dwordx4 v[210:213], v131, s[8:9] offset:64
	global_load_dwordx4 v[214:217], v132, s[8:9] offset:64
	v_mul_f32_e32 v134, v93, v93
	v_fmac_f32_e32 v134, v92, v92
	v_fmac_f32_e32 v134, v94, v94
	v_fmac_f32_e32 v134, v95, v95
	v_fmac_f32_e32 v134, v88, v88
	v_fmac_f32_e32 v134, v89, v89
	v_fmac_f32_e32 v134, v90, v90
	v_fmac_f32_e32 v134, v91, v91
	v_fmac_f32_e32 v134, v84, v84
	v_fmac_f32_e32 v134, v85, v85
	v_pk_mul_f32 v[136:137], v[86:87], v[86:87]
	v_pk_mul_f32 v[138:139], v[80:81], v[80:81]
	v_add_f32_e32 v134, v136, v134
	v_add_f32_e32 v134, v137, v134
	v_add_f32_e32 v134, v138, v134
	v_pk_mul_f32 v[136:137], v[82:83], v[82:83]
	v_add_f32_e32 v134, v139, v134
	v_add_f32_e32 v134, v136, v134
	v_add_f32_e32 v134, v137, v134
	ds_swizzle_b32 v135, v134 offset:swizzle(SWAP,16)
	s_waitcnt lgkmcnt(0)
	v_add_f32_e32 v134, v134, v135
	v_mov_b32_e32 v135, v134
	s_nop 1
	v_permlane32_swap_b32 v134, v135
	s_nop 1
	v_add_f32_e32 v134, v134, v135
	v_fmamk_f32 v134, v134, 0x3c800000, v242
	v_rsq_f32_e32 v134, v134
	s_nop 0
	v_pk_mul_f32 v[136:137], v[134:135], v[148:149] op_sel_hi:[0,1]
	v_pk_mul_f32 v[92:93], v[92:93], v[136:137]
	v_pk_mul_f32 v[136:137], v[134:135], v[150:151] op_sel_hi:[0,1]
	v_pk_mul_f32 v[94:95], v[94:95], v[136:137]
	v_pk_mul_f32 v[136:137], v[134:135], v[152:153] op_sel_hi:[0,1]
	v_pk_mul_f32 v[88:89], v[88:89], v[136:137]
	v_pk_mul_f32 v[136:137], v[134:135], v[154:155] op_sel_hi:[0,1]
	v_pk_mul_f32 v[90:91], v[90:91], v[136:137]
	v_pk_mul_f32 v[136:137], v[134:135], v[156:157] op_sel_hi:[0,1]
	v_pk_mul_f32 v[84:85], v[84:85], v[136:137]
	v_pk_mul_f32 v[136:137], v[134:135], v[158:159] op_sel_hi:[0,1]
	v_pk_mul_f32 v[86:87], v[86:87], v[136:137]
	v_pk_mul_f32 v[136:137], v[134:135], v[160:161] op_sel_hi:[0,1]
	v_pk_mul_f32 v[80:81], v[80:81], v[136:137]
	v_pk_mul_f32 v[136:137], v[134:135], v[162:163] op_sel_hi:[0,1]
	v_pk_mul_f32 v[82:83], v[82:83], v[136:137]
	s_waitcnt vmcnt(6)
	v_pk_mul_f32 v[136:137], v[92:93], v[168:169] op_sel:[1,0] op_sel_hi:[0,0]
	v_pk_fma_f32 v[92:93], v[92:93], v[164:165], v[136:137] op_sel:[0,0,0] op_sel_hi:[1,0,1] neg_lo:[0,0,1]
	v_pk_mul_f32 v[136:137], v[94:95], v[168:169] op_sel:[1,1] op_sel_hi:[0,1]
	v_pk_fma_f32 v[94:95], v[94:95], v[164:165], v[136:137] op_sel:[0,1,0] op_sel_hi:[1,1,1] neg_lo:[0,0,1]
	v_pk_mul_f32 v[136:137], v[88:89], v[170:171] op_sel:[1,0] op_sel_hi:[0,0]
	v_pk_fma_f32 v[88:89], v[88:89], v[166:167], v[136:137] op_sel:[0,0,0] op_sel_hi:[1,0,1] neg_lo:[0,0,1]
	v_pk_mul_f32 v[136:137], v[90:91], v[170:171] op_sel:[1,1] op_sel_hi:[0,1]
	v_pk_fma_f32 v[90:91], v[90:91], v[166:167], v[136:137] op_sel:[0,1,0] op_sel_hi:[1,1,1] neg_lo:[0,0,1]
	v_pk_mul_f32 v[92:93], v[92:93], s[36:37] op_sel_hi:[1,0]
	v_pk_mul_f32 v[94:95], v[94:95], s[36:37] op_sel_hi:[1,0]
	v_pk_mul_f32 v[88:89], v[88:89], s[36:37] op_sel_hi:[1,0]
	v_pk_mul_f32 v[90:91], v[90:91], s[36:37] op_sel_hi:[1,0]
	v_cvt_pk_bf16_f32 v140, v92, v93
	v_cvt_pk_bf16_f32 v141, v94, v95
	v_cvt_pk_bf16_f32 v142, v88, v89
	v_cvt_pk_bf16_f32 v143, v90, v91
	global_store_dwordx4 v130, v[140:143], s[6:7]
	v_pk_mul_f32 v[136:137], v[84:85], v[176:177] op_sel:[1,0] op_sel_hi:[0,0]
	v_pk_fma_f32 v[84:85], v[84:85], v[172:173], v[136:137] op_sel:[0,0,0] op_sel_hi:[1,0,1] neg_lo:[0,0,1]
	v_pk_mul_f32 v[136:137], v[86:87], v[176:177] op_sel:[1,1] op_sel_hi:[0,1]
	v_pk_fma_f32 v[86:87], v[86:87], v[172:173], v[136:137] op_sel:[0,1,0] op_sel_hi:[1,1,1] neg_lo:[0,0,1]
	v_pk_mul_f32 v[136:137], v[80:81], v[178:179] op_sel:[1,0] op_sel_hi:[0,0]
	v_pk_fma_f32 v[80:81], v[80:81], v[174:175], v[136:137] op_sel:[0,0,0] op_sel_hi:[1,0,1] neg_lo:[0,0,1]
	v_pk_mul_f32 v[136:137], v[82:83], v[178:179] op_sel:[1,1] op_sel_hi:[0,1]
	v_pk_fma_f32 v[82:83], v[82:83], v[174:175], v[136:137] op_sel:[0,1,0] op_sel_hi:[1,1,1] neg_lo:[0,0,1]
	v_pk_mul_f32 v[84:85], v[84:85], s[36:37] op_sel_hi:[1,0]
	v_pk_mul_f32 v[86:87], v[86:87], s[36:37] op_sel_hi:[1,0]
	v_pk_mul_f32 v[80:81], v[80:81], s[36:37] op_sel_hi:[1,0]
	v_pk_mul_f32 v[82:83], v[82:83], s[36:37] op_sel_hi:[1,0]
	v_cvt_pk_bf16_f32 v144, v84, v85
	v_cvt_pk_bf16_f32 v145, v86, v87
	v_cvt_pk_bf16_f32 v146, v80, v81
	v_cvt_pk_bf16_f32 v147, v82, v83
	global_store_dwordx4 v130, v[144:147], s[6:7] offset:64
	s_add_u32 s6, s6, s33
	s_addc_u32 s7, s7, 0
	s_add_u32 s8, s8, 0x2800
	s_addc_u32 s9, s9, 0
	global_load_dwordx4 v[164:167], v131, s[8:9]
	global_load_dwordx4 v[168:171], v132, s[8:9]
	global_load_dwordx4 v[172:175], v131, s[8:9] offset:64
	global_load_dwordx4 v[176:179], v132, s[8:9] offset:64
	v_mul_f32_e32 v134, v77, v77
	v_fmac_f32_e32 v134, v76, v76
	v_fmac_f32_e32 v134, v78, v78
	v_fmac_f32_e32 v134, v79, v79
	v_fmac_f32_e32 v134, v72, v72
	v_fmac_f32_e32 v134, v73, v73
	v_fmac_f32_e32 v134, v74, v74
	v_fmac_f32_e32 v134, v75, v75
	v_fmac_f32_e32 v134, v68, v68
	v_fmac_f32_e32 v134, v69, v69
	v_pk_mul_f32 v[136:137], v[70:71], v[70:71]
	v_pk_mul_f32 v[138:139], v[64:65], v[64:65]
	v_add_f32_e32 v134, v136, v134
	v_add_f32_e32 v134, v137, v134
	v_add_f32_e32 v134, v138, v134
	v_pk_mul_f32 v[136:137], v[66:67], v[66:67]
	v_add_f32_e32 v134, v139, v134
	v_add_f32_e32 v134, v136, v134
	v_add_f32_e32 v134, v137, v134
	ds_swizzle_b32 v135, v134 offset:swizzle(SWAP,16)
	s_waitcnt lgkmcnt(0)
	v_add_f32_e32 v134, v134, v135
	v_mov_b32_e32 v135, v134
	s_nop 1
	v_permlane32_swap_b32 v134, v135
	s_nop 1
	v_add_f32_e32 v134, v134, v135
	v_fmamk_f32 v134, v134, 0x3c800000, v242
	v_rsq_f32_e32 v134, v134
	s_nop 0
	v_pk_mul_f32 v[136:137], v[134:135], v[148:149] op_sel_hi:[0,1]
	v_pk_mul_f32 v[76:77], v[76:77], v[136:137]
	v_pk_mul_f32 v[136:137], v[134:135], v[150:151] op_sel_hi:[0,1]
	v_pk_mul_f32 v[78:79], v[78:79], v[136:137]
	v_pk_mul_f32 v[136:137], v[134:135], v[152:153] op_sel_hi:[0,1]
	v_pk_mul_f32 v[72:73], v[72:73], v[136:137]
	v_pk_mul_f32 v[136:137], v[134:135], v[154:155] op_sel_hi:[0,1]
	v_pk_mul_f32 v[74:75], v[74:75], v[136:137]
	v_pk_mul_f32 v[136:137], v[134:135], v[156:157] op_sel_hi:[0,1]
	v_pk_mul_f32 v[68:69], v[68:69], v[136:137]
	v_pk_mul_f32 v[136:137], v[134:135], v[158:159] op_sel_hi:[0,1]
	v_pk_mul_f32 v[70:71], v[70:71], v[136:137]
	v_pk_mul_f32 v[136:137], v[134:135], v[160:161] op_sel_hi:[0,1]
	v_pk_mul_f32 v[64:65], v[64:65], v[136:137]
	v_pk_mul_f32 v[136:137], v[134:135], v[162:163] op_sel_hi:[0,1]
	v_pk_mul_f32 v[66:67], v[66:67], v[136:137]
	s_waitcnt vmcnt(6)
	v_pk_mul_f32 v[136:137], v[76:77], v[206:207] op_sel:[1,0] op_sel_hi:[0,0]
	v_pk_fma_f32 v[76:77], v[76:77], v[202:203], v[136:137] op_sel:[0,0,0] op_sel_hi:[1,0,1] neg_lo:[0,0,1]
	v_pk_mul_f32 v[136:137], v[78:79], v[206:207] op_sel:[1,1] op_sel_hi:[0,1]
	v_pk_fma_f32 v[78:79], v[78:79], v[202:203], v[136:137] op_sel:[0,1,0] op_sel_hi:[1,1,1] neg_lo:[0,0,1]
	v_pk_mul_f32 v[136:137], v[72:73], v[208:209] op_sel:[1,0] op_sel_hi:[0,0]
	v_pk_fma_f32 v[72:73], v[72:73], v[204:205], v[136:137] op_sel:[0,0,0] op_sel_hi:[1,0,1] neg_lo:[0,0,1]
	v_pk_mul_f32 v[136:137], v[74:75], v[208:209] op_sel:[1,1] op_sel_hi:[0,1]
	v_pk_fma_f32 v[74:75], v[74:75], v[204:205], v[136:137] op_sel:[0,1,0] op_sel_hi:[1,1,1] neg_lo:[0,0,1]
	v_pk_mul_f32 v[76:77], v[76:77], s[36:37] op_sel_hi:[1,0]
	v_pk_mul_f32 v[78:79], v[78:79], s[36:37] op_sel_hi:[1,0]
	v_pk_mul_f32 v[72:73], v[72:73], s[36:37] op_sel_hi:[1,0]
	v_pk_mul_f32 v[74:75], v[74:75], s[36:37] op_sel_hi:[1,0]
	v_cvt_pk_bf16_f32 v140, v76, v77
	v_cvt_pk_bf16_f32 v141, v78, v79
	v_cvt_pk_bf16_f32 v142, v72, v73
	v_cvt_pk_bf16_f32 v143, v74, v75
	global_store_dwordx4 v130, v[140:143], s[6:7]
	v_pk_mul_f32 v[136:137], v[68:69], v[214:215] op_sel:[1,0] op_sel_hi:[0,0]
	v_pk_fma_f32 v[68:69], v[68:69], v[210:211], v[136:137] op_sel:[0,0,0] op_sel_hi:[1,0,1] neg_lo:[0,0,1]
	v_pk_mul_f32 v[136:137], v[70:71], v[214:215] op_sel:[1,1] op_sel_hi:[0,1]
	v_pk_fma_f32 v[70:71], v[70:71], v[210:211], v[136:137] op_sel:[0,1,0] op_sel_hi:[1,1,1] neg_lo:[0,0,1]
	v_pk_mul_f32 v[136:137], v[64:65], v[216:217] op_sel:[1,0] op_sel_hi:[0,0]
	v_pk_fma_f32 v[64:65], v[64:65], v[212:213], v[136:137] op_sel:[0,0,0] op_sel_hi:[1,0,1] neg_lo:[0,0,1]
	v_pk_mul_f32 v[136:137], v[66:67], v[216:217] op_sel:[1,1] op_sel_hi:[0,1]
	v_pk_fma_f32 v[66:67], v[66:67], v[212:213], v[136:137] op_sel:[0,1,0] op_sel_hi:[1,1,1] neg_lo:[0,0,1]
	v_pk_mul_f32 v[68:69], v[68:69], s[36:37] op_sel_hi:[1,0]
	v_pk_mul_f32 v[70:71], v[70:71], s[36:37] op_sel_hi:[1,0]
	v_pk_mul_f32 v[64:65], v[64:65], s[36:37] op_sel_hi:[1,0]
	v_pk_mul_f32 v[66:67], v[66:67], s[36:37] op_sel_hi:[1,0]
	v_cvt_pk_bf16_f32 v144, v68, v69
	v_cvt_pk_bf16_f32 v145, v70, v71
	v_cvt_pk_bf16_f32 v146, v64, v65
	v_cvt_pk_bf16_f32 v147, v66, v67
	global_store_dwordx4 v130, v[144:147], s[6:7] offset:64
	s_add_u32 s6, s6, s34
	s_addc_u32 s7, s7, 0
	s_add_u32 s8, s8, 0x800
	s_addc_u32 s9, s9, 0
	global_load_dwordx4 v[202:205], v131, s[8:9]
	global_load_dwordx4 v[206:209], v132, s[8:9]
	global_load_dwordx4 v[210:213], v131, s[8:9] offset:64
	global_load_dwordx4 v[214:217], v132, s[8:9] offset:64
	v_mul_f32_e32 v134, v61, v61
	v_fmac_f32_e32 v134, v60, v60
	v_fmac_f32_e32 v134, v62, v62
	v_fmac_f32_e32 v134, v63, v63
	v_fmac_f32_e32 v134, v56, v56
	v_fmac_f32_e32 v134, v57, v57
	v_fmac_f32_e32 v134, v58, v58
	v_fmac_f32_e32 v134, v59, v59
	v_fmac_f32_e32 v134, v52, v52
	v_fmac_f32_e32 v134, v53, v53
	v_pk_mul_f32 v[136:137], v[54:55], v[54:55]
	v_pk_mul_f32 v[138:139], v[48:49], v[48:49]
	v_add_f32_e32 v134, v136, v134
	v_add_f32_e32 v134, v137, v134
	v_add_f32_e32 v134, v138, v134
	v_pk_mul_f32 v[136:137], v[50:51], v[50:51]
	v_add_f32_e32 v134, v139, v134
	v_add_f32_e32 v134, v136, v134
	v_add_f32_e32 v134, v137, v134
	ds_swizzle_b32 v135, v134 offset:swizzle(SWAP,16)
	s_waitcnt lgkmcnt(0)
	v_add_f32_e32 v134, v134, v135
	v_mov_b32_e32 v135, v134
	s_nop 1
	v_permlane32_swap_b32 v134, v135
	s_nop 1
	v_add_f32_e32 v134, v134, v135
	v_fmamk_f32 v134, v134, 0x3c800000, v242
	v_rsq_f32_e32 v134, v134
	s_nop 0
	v_pk_mul_f32 v[136:137], v[134:135], v[148:149] op_sel_hi:[0,1]
	v_pk_mul_f32 v[60:61], v[60:61], v[136:137]
	v_pk_mul_f32 v[136:137], v[134:135], v[150:151] op_sel_hi:[0,1]
	v_pk_mul_f32 v[62:63], v[62:63], v[136:137]
	v_pk_mul_f32 v[136:137], v[134:135], v[152:153] op_sel_hi:[0,1]
	v_pk_mul_f32 v[56:57], v[56:57], v[136:137]
	v_pk_mul_f32 v[136:137], v[134:135], v[154:155] op_sel_hi:[0,1]
	v_pk_mul_f32 v[58:59], v[58:59], v[136:137]
	v_pk_mul_f32 v[136:137], v[134:135], v[156:157] op_sel_hi:[0,1]
	v_pk_mul_f32 v[52:53], v[52:53], v[136:137]
	v_pk_mul_f32 v[136:137], v[134:135], v[158:159] op_sel_hi:[0,1]
	v_pk_mul_f32 v[54:55], v[54:55], v[136:137]
	v_pk_mul_f32 v[136:137], v[134:135], v[160:161] op_sel_hi:[0,1]
	v_pk_mul_f32 v[48:49], v[48:49], v[136:137]
	v_pk_mul_f32 v[136:137], v[134:135], v[162:163] op_sel_hi:[0,1]
	v_pk_mul_f32 v[50:51], v[50:51], v[136:137]
	s_waitcnt vmcnt(6)
	v_pk_mul_f32 v[136:137], v[60:61], v[168:169] op_sel:[1,0] op_sel_hi:[0,0]
	v_pk_fma_f32 v[60:61], v[60:61], v[164:165], v[136:137] op_sel:[0,0,0] op_sel_hi:[1,0,1] neg_lo:[0,0,1]
	v_pk_mul_f32 v[136:137], v[62:63], v[168:169] op_sel:[1,1] op_sel_hi:[0,1]
	v_pk_fma_f32 v[62:63], v[62:63], v[164:165], v[136:137] op_sel:[0,1,0] op_sel_hi:[1,1,1] neg_lo:[0,0,1]
	v_pk_mul_f32 v[136:137], v[56:57], v[170:171] op_sel:[1,0] op_sel_hi:[0,0]
	v_pk_fma_f32 v[56:57], v[56:57], v[166:167], v[136:137] op_sel:[0,0,0] op_sel_hi:[1,0,1] neg_lo:[0,0,1]
	v_pk_mul_f32 v[136:137], v[58:59], v[170:171] op_sel:[1,1] op_sel_hi:[0,1]
	v_pk_fma_f32 v[58:59], v[58:59], v[166:167], v[136:137] op_sel:[0,1,0] op_sel_hi:[1,1,1] neg_lo:[0,0,1]
	v_pk_mul_f32 v[60:61], v[60:61], s[36:37] op_sel_hi:[1,0]
	v_pk_mul_f32 v[62:63], v[62:63], s[36:37] op_sel_hi:[1,0]
	v_pk_mul_f32 v[56:57], v[56:57], s[36:37] op_sel_hi:[1,0]
	v_pk_mul_f32 v[58:59], v[58:59], s[36:37] op_sel_hi:[1,0]
	v_cvt_pk_bf16_f32 v140, v60, v61
	v_cvt_pk_bf16_f32 v141, v62, v63
	v_cvt_pk_bf16_f32 v142, v56, v57
	v_cvt_pk_bf16_f32 v143, v58, v59
	global_store_dwordx4 v130, v[140:143], s[6:7]
	v_pk_mul_f32 v[136:137], v[52:53], v[176:177] op_sel:[1,0] op_sel_hi:[0,0]
	v_pk_fma_f32 v[52:53], v[52:53], v[172:173], v[136:137] op_sel:[0,0,0] op_sel_hi:[1,0,1] neg_lo:[0,0,1]
	v_pk_mul_f32 v[136:137], v[54:55], v[176:177] op_sel:[1,1] op_sel_hi:[0,1]
	v_pk_fma_f32 v[54:55], v[54:55], v[172:173], v[136:137] op_sel:[0,1,0] op_sel_hi:[1,1,1] neg_lo:[0,0,1]
	v_pk_mul_f32 v[136:137], v[48:49], v[178:179] op_sel:[1,0] op_sel_hi:[0,0]
	v_pk_fma_f32 v[48:49], v[48:49], v[174:175], v[136:137] op_sel:[0,0,0] op_sel_hi:[1,0,1] neg_lo:[0,0,1]
	v_pk_mul_f32 v[136:137], v[50:51], v[178:179] op_sel:[1,1] op_sel_hi:[0,1]
	v_pk_fma_f32 v[50:51], v[50:51], v[174:175], v[136:137] op_sel:[0,1,0] op_sel_hi:[1,1,1] neg_lo:[0,0,1]
	v_pk_mul_f32 v[52:53], v[52:53], s[36:37] op_sel_hi:[1,0]
	v_pk_mul_f32 v[54:55], v[54:55], s[36:37] op_sel_hi:[1,0]
	v_pk_mul_f32 v[48:49], v[48:49], s[36:37] op_sel_hi:[1,0]
	v_pk_mul_f32 v[50:51], v[50:51], s[36:37] op_sel_hi:[1,0]
	v_cvt_pk_bf16_f32 v144, v52, v53
	v_cvt_pk_bf16_f32 v145, v54, v55
	v_cvt_pk_bf16_f32 v146, v48, v49
	v_cvt_pk_bf16_f32 v147, v50, v51
	global_store_dwordx4 v130, v[144:147], s[6:7] offset:64
	s_add_u32 s6, s6, s33
	s_addc_u32 s7, s7, 0
	s_add_u32 s8, s8, 0x800
	s_addc_u32 s9, s9, 0
	global_load_dwordx4 v[164:167], v131, s[8:9]
	global_load_dwordx4 v[168:171], v132, s[8:9]
	global_load_dwordx4 v[172:175], v131, s[8:9] offset:64
	global_load_dwordx4 v[176:179], v132, s[8:9] offset:64
	v_mul_f32_e32 v134, v45, v45
	v_fmac_f32_e32 v134, v44, v44
	v_fmac_f32_e32 v134, v46, v46
	v_fmac_f32_e32 v134, v47, v47
	v_fmac_f32_e32 v134, v40, v40
	v_fmac_f32_e32 v134, v41, v41
	v_fmac_f32_e32 v134, v42, v42
	v_fmac_f32_e32 v134, v43, v43
	v_fmac_f32_e32 v134, v36, v36
	v_fmac_f32_e32 v134, v37, v37
	v_pk_mul_f32 v[136:137], v[38:39], v[38:39]
	v_pk_mul_f32 v[138:139], v[32:33], v[32:33]
	v_add_f32_e32 v134, v136, v134
	v_add_f32_e32 v134, v137, v134
	v_add_f32_e32 v134, v138, v134
	v_pk_mul_f32 v[136:137], v[34:35], v[34:35]
	v_add_f32_e32 v134, v139, v134
	v_add_f32_e32 v134, v136, v134
	v_add_f32_e32 v134, v137, v134
	ds_swizzle_b32 v135, v134 offset:swizzle(SWAP,16)
	s_waitcnt lgkmcnt(0)
	v_add_f32_e32 v134, v134, v135
	v_mov_b32_e32 v135, v134
	s_nop 1
	v_permlane32_swap_b32 v134, v135
	s_nop 1
	v_add_f32_e32 v134, v134, v135
	v_fmamk_f32 v134, v134, 0x3c800000, v242
	v_rsq_f32_e32 v134, v134
	s_nop 0
	v_pk_mul_f32 v[136:137], v[134:135], v[148:149] op_sel_hi:[0,1]
	v_pk_mul_f32 v[44:45], v[44:45], v[136:137]
	v_pk_mul_f32 v[136:137], v[134:135], v[150:151] op_sel_hi:[0,1]
	v_pk_mul_f32 v[46:47], v[46:47], v[136:137]
	v_pk_mul_f32 v[136:137], v[134:135], v[152:153] op_sel_hi:[0,1]
	v_pk_mul_f32 v[40:41], v[40:41], v[136:137]
	v_pk_mul_f32 v[136:137], v[134:135], v[154:155] op_sel_hi:[0,1]
	v_pk_mul_f32 v[42:43], v[42:43], v[136:137]
	v_pk_mul_f32 v[136:137], v[134:135], v[156:157] op_sel_hi:[0,1]
	v_pk_mul_f32 v[36:37], v[36:37], v[136:137]
	v_pk_mul_f32 v[136:137], v[134:135], v[158:159] op_sel_hi:[0,1]
	v_pk_mul_f32 v[38:39], v[38:39], v[136:137]
	v_pk_mul_f32 v[136:137], v[134:135], v[160:161] op_sel_hi:[0,1]
	v_pk_mul_f32 v[32:33], v[32:33], v[136:137]
	v_pk_mul_f32 v[136:137], v[134:135], v[162:163] op_sel_hi:[0,1]
	v_pk_mul_f32 v[34:35], v[34:35], v[136:137]
	s_waitcnt vmcnt(6)
	v_pk_mul_f32 v[136:137], v[44:45], v[206:207] op_sel:[1,0] op_sel_hi:[0,0]
	v_pk_fma_f32 v[44:45], v[44:45], v[202:203], v[136:137] op_sel:[0,0,0] op_sel_hi:[1,0,1] neg_lo:[0,0,1]
	v_pk_mul_f32 v[136:137], v[46:47], v[206:207] op_sel:[1,1] op_sel_hi:[0,1]
	v_pk_fma_f32 v[46:47], v[46:47], v[202:203], v[136:137] op_sel:[0,1,0] op_sel_hi:[1,1,1] neg_lo:[0,0,1]
	v_pk_mul_f32 v[136:137], v[40:41], v[208:209] op_sel:[1,0] op_sel_hi:[0,0]
	v_pk_fma_f32 v[40:41], v[40:41], v[204:205], v[136:137] op_sel:[0,0,0] op_sel_hi:[1,0,1] neg_lo:[0,0,1]
	v_pk_mul_f32 v[136:137], v[42:43], v[208:209] op_sel:[1,1] op_sel_hi:[0,1]
	v_pk_fma_f32 v[42:43], v[42:43], v[204:205], v[136:137] op_sel:[0,1,0] op_sel_hi:[1,1,1] neg_lo:[0,0,1]
	v_pk_mul_f32 v[44:45], v[44:45], s[36:37] op_sel_hi:[1,0]
	v_pk_mul_f32 v[46:47], v[46:47], s[36:37] op_sel_hi:[1,0]
	v_pk_mul_f32 v[40:41], v[40:41], s[36:37] op_sel_hi:[1,0]
	v_pk_mul_f32 v[42:43], v[42:43], s[36:37] op_sel_hi:[1,0]
	v_cvt_pk_bf16_f32 v140, v44, v45
	v_cvt_pk_bf16_f32 v141, v46, v47
	v_cvt_pk_bf16_f32 v142, v40, v41
	v_cvt_pk_bf16_f32 v143, v42, v43
	global_store_dwordx4 v130, v[140:143], s[6:7]
	v_pk_mul_f32 v[136:137], v[36:37], v[214:215] op_sel:[1,0] op_sel_hi:[0,0]
	v_pk_fma_f32 v[36:37], v[36:37], v[210:211], v[136:137] op_sel:[0,0,0] op_sel_hi:[1,0,1] neg_lo:[0,0,1]
	v_pk_mul_f32 v[136:137], v[38:39], v[214:215] op_sel:[1,1] op_sel_hi:[0,1]
	v_pk_fma_f32 v[38:39], v[38:39], v[210:211], v[136:137] op_sel:[0,1,0] op_sel_hi:[1,1,1] neg_lo:[0,0,1]
	v_pk_mul_f32 v[136:137], v[32:33], v[216:217] op_sel:[1,0] op_sel_hi:[0,0]
	v_pk_fma_f32 v[32:33], v[32:33], v[212:213], v[136:137] op_sel:[0,0,0] op_sel_hi:[1,0,1] neg_lo:[0,0,1]
	v_pk_mul_f32 v[136:137], v[34:35], v[216:217] op_sel:[1,1] op_sel_hi:[0,1]
	v_pk_fma_f32 v[34:35], v[34:35], v[212:213], v[136:137] op_sel:[0,1,0] op_sel_hi:[1,1,1] neg_lo:[0,0,1]
	v_pk_mul_f32 v[36:37], v[36:37], s[36:37] op_sel_hi:[1,0]
	v_pk_mul_f32 v[38:39], v[38:39], s[36:37] op_sel_hi:[1,0]
	v_pk_mul_f32 v[32:33], v[32:33], s[36:37] op_sel_hi:[1,0]
	v_pk_mul_f32 v[34:35], v[34:35], s[36:37] op_sel_hi:[1,0]
	v_cvt_pk_bf16_f32 v144, v36, v37
	v_cvt_pk_bf16_f32 v145, v38, v39
	v_cvt_pk_bf16_f32 v146, v32, v33
	v_cvt_pk_bf16_f32 v147, v34, v35
	global_store_dwordx4 v130, v[144:147], s[6:7] offset:64
	s_add_u32 s6, s6, s33
	s_addc_u32 s7, s7, 0
	s_add_u32 s8, s8, 0x800
	s_addc_u32 s9, s9, 0
	global_load_dwordx4 v[202:205], v131, s[8:9]
	global_load_dwordx4 v[206:209], v132, s[8:9]
	global_load_dwordx4 v[210:213], v131, s[8:9] offset:64
	global_load_dwordx4 v[214:217], v132, s[8:9] offset:64
	v_mul_f32_e32 v134, v29, v29
	v_fmac_f32_e32 v134, v28, v28
	v_fmac_f32_e32 v134, v30, v30
	v_fmac_f32_e32 v134, v31, v31
	v_fmac_f32_e32 v134, v24, v24
	v_fmac_f32_e32 v134, v25, v25
	v_fmac_f32_e32 v134, v26, v26
	v_fmac_f32_e32 v134, v27, v27
	v_fmac_f32_e32 v134, v20, v20
	v_fmac_f32_e32 v134, v21, v21
	v_pk_mul_f32 v[136:137], v[22:23], v[22:23]
	v_pk_mul_f32 v[138:139], v[16:17], v[16:17]
	v_add_f32_e32 v134, v136, v134
	v_add_f32_e32 v134, v137, v134
	v_add_f32_e32 v134, v138, v134
	v_pk_mul_f32 v[136:137], v[18:19], v[18:19]
	v_add_f32_e32 v134, v139, v134
	v_add_f32_e32 v134, v136, v134
	v_add_f32_e32 v134, v137, v134
	ds_swizzle_b32 v135, v134 offset:swizzle(SWAP,16)
	s_waitcnt lgkmcnt(0)
	v_add_f32_e32 v134, v134, v135
	v_mov_b32_e32 v135, v134
	s_nop 1
	v_permlane32_swap_b32 v134, v135
	s_nop 1
	v_add_f32_e32 v134, v134, v135
	v_fmamk_f32 v134, v134, 0x3c800000, v242
	v_rsq_f32_e32 v134, v134
	s_nop 0
	v_pk_mul_f32 v[136:137], v[134:135], v[148:149] op_sel_hi:[0,1]
	v_pk_mul_f32 v[28:29], v[28:29], v[136:137]
	v_pk_mul_f32 v[136:137], v[134:135], v[150:151] op_sel_hi:[0,1]
	v_pk_mul_f32 v[30:31], v[30:31], v[136:137]
	v_pk_mul_f32 v[136:137], v[134:135], v[152:153] op_sel_hi:[0,1]
	v_pk_mul_f32 v[24:25], v[24:25], v[136:137]
	v_pk_mul_f32 v[136:137], v[134:135], v[154:155] op_sel_hi:[0,1]
	v_pk_mul_f32 v[26:27], v[26:27], v[136:137]
	v_pk_mul_f32 v[136:137], v[134:135], v[156:157] op_sel_hi:[0,1]
	v_pk_mul_f32 v[20:21], v[20:21], v[136:137]
	v_pk_mul_f32 v[136:137], v[134:135], v[158:159] op_sel_hi:[0,1]
	v_pk_mul_f32 v[22:23], v[22:23], v[136:137]
	v_pk_mul_f32 v[136:137], v[134:135], v[160:161] op_sel_hi:[0,1]
	v_pk_mul_f32 v[16:17], v[16:17], v[136:137]
	v_pk_mul_f32 v[136:137], v[134:135], v[162:163] op_sel_hi:[0,1]
	v_pk_mul_f32 v[18:19], v[18:19], v[136:137]
	s_waitcnt vmcnt(6)
	v_pk_mul_f32 v[136:137], v[28:29], v[168:169] op_sel:[1,0] op_sel_hi:[0,0]
	v_pk_fma_f32 v[28:29], v[28:29], v[164:165], v[136:137] op_sel:[0,0,0] op_sel_hi:[1,0,1] neg_lo:[0,0,1]
	v_pk_mul_f32 v[136:137], v[30:31], v[168:169] op_sel:[1,1] op_sel_hi:[0,1]
	v_pk_fma_f32 v[30:31], v[30:31], v[164:165], v[136:137] op_sel:[0,1,0] op_sel_hi:[1,1,1] neg_lo:[0,0,1]
	v_pk_mul_f32 v[136:137], v[24:25], v[170:171] op_sel:[1,0] op_sel_hi:[0,0]
	v_pk_fma_f32 v[24:25], v[24:25], v[166:167], v[136:137] op_sel:[0,0,0] op_sel_hi:[1,0,1] neg_lo:[0,0,1]
	v_pk_mul_f32 v[136:137], v[26:27], v[170:171] op_sel:[1,1] op_sel_hi:[0,1]
	v_pk_fma_f32 v[26:27], v[26:27], v[166:167], v[136:137] op_sel:[0,1,0] op_sel_hi:[1,1,1] neg_lo:[0,0,1]
	v_pk_mul_f32 v[28:29], v[28:29], s[36:37] op_sel_hi:[1,0]
	v_pk_mul_f32 v[30:31], v[30:31], s[36:37] op_sel_hi:[1,0]
	v_pk_mul_f32 v[24:25], v[24:25], s[36:37] op_sel_hi:[1,0]
	v_pk_mul_f32 v[26:27], v[26:27], s[36:37] op_sel_hi:[1,0]
	v_cvt_pk_bf16_f32 v140, v28, v29
	v_cvt_pk_bf16_f32 v141, v30, v31
	v_cvt_pk_bf16_f32 v142, v24, v25
	v_cvt_pk_bf16_f32 v143, v26, v27
	global_store_dwordx4 v130, v[140:143], s[6:7]
	v_pk_mul_f32 v[136:137], v[20:21], v[176:177] op_sel:[1,0] op_sel_hi:[0,0]
	v_pk_fma_f32 v[20:21], v[20:21], v[172:173], v[136:137] op_sel:[0,0,0] op_sel_hi:[1,0,1] neg_lo:[0,0,1]
	v_pk_mul_f32 v[136:137], v[22:23], v[176:177] op_sel:[1,1] op_sel_hi:[0,1]
	v_pk_fma_f32 v[22:23], v[22:23], v[172:173], v[136:137] op_sel:[0,1,0] op_sel_hi:[1,1,1] neg_lo:[0,0,1]
	v_pk_mul_f32 v[136:137], v[16:17], v[178:179] op_sel:[1,0] op_sel_hi:[0,0]
	v_pk_fma_f32 v[16:17], v[16:17], v[174:175], v[136:137] op_sel:[0,0,0] op_sel_hi:[1,0,1] neg_lo:[0,0,1]
	v_pk_mul_f32 v[136:137], v[18:19], v[178:179] op_sel:[1,1] op_sel_hi:[0,1]
	v_pk_fma_f32 v[18:19], v[18:19], v[174:175], v[136:137] op_sel:[0,1,0] op_sel_hi:[1,1,1] neg_lo:[0,0,1]
	v_pk_mul_f32 v[20:21], v[20:21], s[36:37] op_sel_hi:[1,0]
	v_pk_mul_f32 v[22:23], v[22:23], s[36:37] op_sel_hi:[1,0]
	v_pk_mul_f32 v[16:17], v[16:17], s[36:37] op_sel_hi:[1,0]
	v_pk_mul_f32 v[18:19], v[18:19], s[36:37] op_sel_hi:[1,0]
	v_cvt_pk_bf16_f32 v144, v20, v21
	v_cvt_pk_bf16_f32 v145, v22, v23
	v_cvt_pk_bf16_f32 v146, v16, v17
	v_cvt_pk_bf16_f32 v147, v18, v19
	global_store_dwordx4 v130, v[144:147], s[6:7] offset:64
	s_add_u32 s6, s6, s33
	s_addc_u32 s7, s7, 0
	v_mul_f32_e32 v134, v13, v13
	v_fmac_f32_e32 v134, v12, v12
	v_fmac_f32_e32 v134, v14, v14
	v_fmac_f32_e32 v134, v15, v15
	v_fmac_f32_e32 v134, v4, v4
	v_fmac_f32_e32 v134, v5, v5
	v_fmac_f32_e32 v134, v6, v6
	v_fmac_f32_e32 v134, v7, v7
	v_fmac_f32_e32 v134, v8, v8
	v_fmac_f32_e32 v134, v9, v9
	v_pk_mul_f32 v[136:137], v[10:11], v[10:11]
	v_pk_mul_f32 v[138:139], v[0:1], v[0:1]
	v_add_f32_e32 v134, v136, v134
	v_add_f32_e32 v134, v137, v134
	v_add_f32_e32 v134, v138, v134
	v_pk_mul_f32 v[136:137], v[2:3], v[2:3]
	v_add_f32_e32 v134, v139, v134
	v_add_f32_e32 v134, v136, v134
	v_add_f32_e32 v134, v137, v134
	ds_swizzle_b32 v135, v134 offset:swizzle(SWAP,16)
	s_waitcnt lgkmcnt(0)
	v_add_f32_e32 v134, v134, v135
	v_mov_b32_e32 v135, v134
	s_nop 1
	v_permlane32_swap_b32 v134, v135
	s_nop 1
	v_add_f32_e32 v134, v134, v135
	v_fmamk_f32 v134, v134, 0x3c800000, v242
	v_rsq_f32_e32 v134, v134
	s_nop 0
	v_pk_mul_f32 v[136:137], v[134:135], v[148:149] op_sel_hi:[0,1]
	v_pk_mul_f32 v[12:13], v[12:13], v[136:137]
	v_pk_mul_f32 v[136:137], v[134:135], v[150:151] op_sel_hi:[0,1]
	v_pk_mul_f32 v[14:15], v[14:15], v[136:137]
	v_pk_mul_f32 v[136:137], v[134:135], v[152:153] op_sel_hi:[0,1]
	v_pk_mul_f32 v[4:5], v[4:5], v[136:137]
	v_pk_mul_f32 v[136:137], v[134:135], v[154:155] op_sel_hi:[0,1]
	v_pk_mul_f32 v[6:7], v[6:7], v[136:137]
	v_pk_mul_f32 v[136:137], v[134:135], v[156:157] op_sel_hi:[0,1]
	v_pk_mul_f32 v[8:9], v[8:9], v[136:137]
	v_pk_mul_f32 v[136:137], v[134:135], v[158:159] op_sel_hi:[0,1]
	v_pk_mul_f32 v[10:11], v[10:11], v[136:137]
	v_pk_mul_f32 v[136:137], v[134:135], v[160:161] op_sel_hi:[0,1]
	v_pk_mul_f32 v[0:1], v[0:1], v[136:137]
	v_pk_mul_f32 v[136:137], v[134:135], v[162:163] op_sel_hi:[0,1]
	v_pk_mul_f32 v[2:3], v[2:3], v[136:137]
	s_waitcnt vmcnt(2)
	v_pk_mul_f32 v[136:137], v[12:13], v[206:207] op_sel:[1,0] op_sel_hi:[0,0]
	v_pk_fma_f32 v[12:13], v[12:13], v[202:203], v[136:137] op_sel:[0,0,0] op_sel_hi:[1,0,1] neg_lo:[0,0,1]
	v_pk_mul_f32 v[136:137], v[14:15], v[206:207] op_sel:[1,1] op_sel_hi:[0,1]
	v_pk_fma_f32 v[14:15], v[14:15], v[202:203], v[136:137] op_sel:[0,1,0] op_sel_hi:[1,1,1] neg_lo:[0,0,1]
	v_pk_mul_f32 v[136:137], v[4:5], v[208:209] op_sel:[1,0] op_sel_hi:[0,0]
	v_pk_fma_f32 v[4:5], v[4:5], v[204:205], v[136:137] op_sel:[0,0,0] op_sel_hi:[1,0,1] neg_lo:[0,0,1]
	v_pk_mul_f32 v[136:137], v[6:7], v[208:209] op_sel:[1,1] op_sel_hi:[0,1]
	v_pk_fma_f32 v[6:7], v[6:7], v[204:205], v[136:137] op_sel:[0,1,0] op_sel_hi:[1,1,1] neg_lo:[0,0,1]
	v_pk_mul_f32 v[12:13], v[12:13], s[36:37] op_sel_hi:[1,0]
	v_pk_mul_f32 v[14:15], v[14:15], s[36:37] op_sel_hi:[1,0]
	v_pk_mul_f32 v[4:5], v[4:5], s[36:37] op_sel_hi:[1,0]
	v_pk_mul_f32 v[6:7], v[6:7], s[36:37] op_sel_hi:[1,0]
	v_cvt_pk_bf16_f32 v140, v12, v13
	v_cvt_pk_bf16_f32 v141, v14, v15
	v_cvt_pk_bf16_f32 v142, v4, v5
	v_cvt_pk_bf16_f32 v143, v6, v7
	global_store_dwordx4 v130, v[140:143], s[6:7]
	v_pk_mul_f32 v[136:137], v[8:9], v[214:215] op_sel:[1,0] op_sel_hi:[0,0]
	v_pk_fma_f32 v[8:9], v[8:9], v[210:211], v[136:137] op_sel:[0,0,0] op_sel_hi:[1,0,1] neg_lo:[0,0,1]
	v_pk_mul_f32 v[136:137], v[10:11], v[214:215] op_sel:[1,1] op_sel_hi:[0,1]
	v_pk_fma_f32 v[10:11], v[10:11], v[210:211], v[136:137] op_sel:[0,1,0] op_sel_hi:[1,1,1] neg_lo:[0,0,1]
	v_pk_mul_f32 v[136:137], v[0:1], v[216:217] op_sel:[1,0] op_sel_hi:[0,0]
	v_pk_fma_f32 v[0:1], v[0:1], v[212:213], v[136:137] op_sel:[0,0,0] op_sel_hi:[1,0,1] neg_lo:[0,0,1]
	v_pk_mul_f32 v[136:137], v[2:3], v[216:217] op_sel:[1,1] op_sel_hi:[0,1]
	v_pk_fma_f32 v[2:3], v[2:3], v[212:213], v[136:137] op_sel:[0,1,0] op_sel_hi:[1,1,1] neg_lo:[0,0,1]
	v_pk_mul_f32 v[8:9], v[8:9], s[36:37] op_sel_hi:[1,0]
	v_pk_mul_f32 v[10:11], v[10:11], s[36:37] op_sel_hi:[1,0]
	v_pk_mul_f32 v[0:1], v[0:1], s[36:37] op_sel_hi:[1,0]
	v_pk_mul_f32 v[2:3], v[2:3], s[36:37] op_sel_hi:[1,0]
	v_cvt_pk_bf16_f32 v144, v8, v9
	v_cvt_pk_bf16_f32 v145, v10, v11
	v_cvt_pk_bf16_f32 v146, v0, v1
	v_cvt_pk_bf16_f32 v147, v2, v3
	global_store_dwordx4 v130, v[144:147], s[6:7] offset:64
	s_branch .LBB0_638
.Lq3_B:
	global_load_dwordx4 v[148:151], v133, s[24:25]
	global_load_dwordx4 v[152:155], v133, s[24:25] offset:16
	global_load_dwordx4 v[156:159], v133, s[24:25] offset:128
	global_load_dwordx4 v[160:163], v133, s[24:25] offset:144
	v_mul_f32_e32 v134, v127, v127
	v_fmac_f32_e32 v134, v126, v126
	v_fmac_f32_e32 v134, v128, v128
	v_fmac_f32_e32 v134, v129, v129
	v_fmac_f32_e32 v134, v122, v122
	v_fmac_f32_e32 v134, v123, v123
	v_fmac_f32_e32 v134, v124, v124
	v_fmac_f32_e32 v134, v125, v125
	v_fmac_f32_e32 v134, v118, v118
	v_fmac_f32_e32 v134, v119, v119
	v_pk_mul_f32 v[136:137], v[120:121], v[120:121]
	v_pk_mul_f32 v[138:139], v[114:115], v[114:115]
	v_add_f32_e32 v134, v136, v134
	v_add_f32_e32 v134, v137, v134
	v_add_f32_e32 v134, v138, v134
	v_pk_mul_f32 v[136:137], v[116:117], v[116:117]
	v_add_f32_e32 v134, v139, v134
	v_add_f32_e32 v134, v136, v134
	v_add_f32_e32 v134, v137, v134
	ds_swizzle_b32 v135, v134 offset:swizzle(SWAP,16)
	s_waitcnt lgkmcnt(0)
	v_add_f32_e32 v134, v134, v135
	v_mov_b32_e32 v135, v134
	s_nop 1
	v_permlane32_swap_b32 v134, v135
	s_nop 1
	v_add_f32_e32 v134, v134, v135
	v_fmamk_f32 v134, v134, 0x3c800000, v242
	v_rsq_f32_e32 v134, v134
	s_waitcnt vmcnt(0)
	v_pk_mul_f32 v[136:137], v[134:135], v[148:149] op_sel_hi:[0,1]
	v_pk_mul_f32 v[126:127], v[126:127], v[136:137]
	v_pk_mul_f32 v[136:137], v[134:135], v[150:151] op_sel_hi:[0,1]
	v_pk_mul_f32 v[128:129], v[128:129], v[136:137]
	v_pk_mul_f32 v[136:137], v[134:135], v[152:153] op_sel_hi:[0,1]
	v_pk_mul_f32 v[122:123], v[122:123], v[136:137]
	v_pk_mul_f32 v[136:137], v[134:135], v[154:155] op_sel_hi:[0,1]
	v_pk_mul_f32 v[124:125], v[124:125], v[136:137]
	v_pk_mul_f32 v[136:137], v[134:135], v[156:157] op_sel_hi:[0,1]
	v_pk_mul_f32 v[118:119], v[118:119], v[136:137]
	v_pk_mul_f32 v[136:137], v[134:135], v[158:159] op_sel_hi:[0,1]
	v_pk_mul_f32 v[120:121], v[120:121], v[136:137]
	v_pk_mul_f32 v[136:137], v[134:135], v[160:161] op_sel_hi:[0,1]
	v_pk_mul_f32 v[114:115], v[114:115], v[136:137]
	v_pk_mul_f32 v[136:137], v[134:135], v[162:163] op_sel_hi:[0,1]
	v_pk_mul_f32 v[116:117], v[116:117], v[136:137]
	v_pk_mul_f32 v[126:127], v[126:127], s[36:37] op_sel_hi:[1,0]
	v_pk_mul_f32 v[128:129], v[128:129], s[36:37] op_sel_hi:[1,0]
	v_pk_mul_f32 v[122:123], v[122:123], s[36:37] op_sel_hi:[1,0]
	v_pk_mul_f32 v[124:125], v[124:125], s[36:37] op_sel_hi:[1,0]
	v_cvt_pk_bf16_f32 v140, v126, v127
	v_cvt_pk_bf16_f32 v141, v128, v129
	v_cvt_pk_bf16_f32 v142, v122, v123
	v_cvt_pk_bf16_f32 v143, v124, v125
	global_store_dwordx4 v130, v[140:143], s[6:7]
	v_pk_mul_f32 v[118:119], v[118:119], s[36:37] op_sel_hi:[1,0]
	v_pk_mul_f32 v[120:121], v[120:121], s[36:37] op_sel_hi:[1,0]
	v_pk_mul_f32 v[114:115], v[114:115], s[36:37] op_sel_hi:[1,0]
	v_pk_mul_f32 v[116:117], v[116:117], s[36:37] op_sel_hi:[1,0]
	v_cvt_pk_bf16_f32 v144, v118, v119
	v_cvt_pk_bf16_f32 v145, v120, v121
	v_cvt_pk_bf16_f32 v146, v114, v115
	v_cvt_pk_bf16_f32 v147, v116, v117
	global_store_dwordx4 v130, v[144:147], s[6:7] offset:64
	s_add_u32 s6, s6, s33
	s_addc_u32 s7, s7, 0
	v_mul_f32_e32 v134, v109, v109
	v_fmac_f32_e32 v134, v108, v108
	v_fmac_f32_e32 v134, v110, v110
	v_fmac_f32_e32 v134, v111, v111
	v_fmac_f32_e32 v134, v104, v104
	v_fmac_f32_e32 v134, v105, v105
	v_fmac_f32_e32 v134, v106, v106
	v_fmac_f32_e32 v134, v107, v107
	v_fmac_f32_e32 v134, v100, v100
	v_fmac_f32_e32 v134, v101, v101
	v_pk_mul_f32 v[136:137], v[102:103], v[102:103]
	v_pk_mul_f32 v[138:139], v[96:97], v[96:97]
	v_add_f32_e32 v134, v136, v134
	v_add_f32_e32 v134, v137, v134
	v_add_f32_e32 v134, v138, v134
	v_pk_mul_f32 v[136:137], v[98:99], v[98:99]
	v_add_f32_e32 v134, v139, v134
	v_add_f32_e32 v134, v136, v134
	v_add_f32_e32 v134, v137, v134
	ds_swizzle_b32 v135, v134 offset:swizzle(SWAP,16)
	s_waitcnt lgkmcnt(0)
	v_add_f32_e32 v134, v134, v135
	v_mov_b32_e32 v135, v134
	s_nop 1
	v_permlane32_swap_b32 v134, v135
	s_nop 1
	v_add_f32_e32 v134, v134, v135
	v_fmamk_f32 v134, v134, 0x3c800000, v242
	v_rsq_f32_e32 v134, v134
	s_nop 0
	v_pk_mul_f32 v[136:137], v[134:135], v[148:149] op_sel_hi:[0,1]
	v_pk_mul_f32 v[108:109], v[108:109], v[136:137]
	v_pk_mul_f32 v[136:137], v[134:135], v[150:151] op_sel_hi:[0,1]
	v_pk_mul_f32 v[110:111], v[110:111], v[136:137]
	v_pk_mul_f32 v[136:137], v[134:135], v[152:153] op_sel_hi:[0,1]
	v_pk_mul_f32 v[104:105], v[104:105], v[136:137]
	v_pk_mul_f32 v[136:137], v[134:135], v[154:155] op_sel_hi:[0,1]
	v_pk_mul_f32 v[106:107], v[106:107], v[136:137]
	v_pk_mul_f32 v[136:137], v[134:135], v[156:157] op_sel_hi:[0,1]
	v_pk_mul_f32 v[100:101], v[100:101], v[136:137]
	v_pk_mul_f32 v[136:137], v[134:135], v[158:159] op_sel_hi:[0,1]
	v_pk_mul_f32 v[102:103], v[102:103], v[136:137]
	v_pk_mul_f32 v[136:137], v[134:135], v[160:161] op_sel_hi:[0,1]
	v_pk_mul_f32 v[96:97], v[96:97], v[136:137]
	v_pk_mul_f32 v[136:137], v[134:135], v[162:163] op_sel_hi:[0,1]
	v_pk_mul_f32 v[98:99], v[98:99], v[136:137]
	v_pk_mul_f32 v[108:109], v[108:109], s[36:37] op_sel_hi:[1,0]
	v_pk_mul_f32 v[110:111], v[110:111], s[36:37] op_sel_hi:[1,0]
	v_pk_mul_f32 v[104:105], v[104:105], s[36:37] op_sel_hi:[1,0]
	v_pk_mul_f32 v[106:107], v[106:107], s[36:37] op_sel_hi:[1,0]
	v_cvt_pk_bf16_f32 v140, v108, v109
	v_cvt_pk_bf16_f32 v141, v110, v111
	v_cvt_pk_bf16_f32 v142, v104, v105
	v_cvt_pk_bf16_f32 v143, v106, v107
	global_store_dwordx4 v130, v[140:143], s[6:7]
	v_pk_mul_f32 v[100:101], v[100:101], s[36:37] op_sel_hi:[1,0]
	v_pk_mul_f32 v[102:103], v[102:103], s[36:37] op_sel_hi:[1,0]
	v_pk_mul_f32 v[96:97], v[96:97], s[36:37] op_sel_hi:[1,0]
	v_pk_mul_f32 v[98:99], v[98:99], s[36:37] op_sel_hi:[1,0]
	v_cvt_pk_bf16_f32 v144, v100, v101
	v_cvt_pk_bf16_f32 v145, v102, v103
	v_cvt_pk_bf16_f32 v146, v96, v97
	v_cvt_pk_bf16_f32 v147, v98, v99
	global_store_dwordx4 v130, v[144:147], s[6:7] offset:64
	s_add_u32 s6, s6, s33
	s_addc_u32 s7, s7, 0
	v_mul_f32_e32 v134, v93, v93
	v_fmac_f32_e32 v134, v92, v92
	v_fmac_f32_e32 v134, v94, v94
	v_fmac_f32_e32 v134, v95, v95
	v_fmac_f32_e32 v134, v88, v88
	v_fmac_f32_e32 v134, v89, v89
	v_fmac_f32_e32 v134, v90, v90
	v_fmac_f32_e32 v134, v91, v91
	v_fmac_f32_e32 v134, v84, v84
	v_fmac_f32_e32 v134, v85, v85
	v_pk_mul_f32 v[136:137], v[86:87], v[86:87]
	v_pk_mul_f32 v[138:139], v[80:81], v[80:81]
	v_add_f32_e32 v134, v136, v134
	v_add_f32_e32 v134, v137, v134
	v_add_f32_e32 v134, v138, v134
	v_pk_mul_f32 v[136:137], v[82:83], v[82:83]
	v_add_f32_e32 v134, v139, v134
	v_add_f32_e32 v134, v136, v134
	v_add_f32_e32 v134, v137, v134
	ds_swizzle_b32 v135, v134 offset:swizzle(SWAP,16)
	s_waitcnt lgkmcnt(0)
	v_add_f32_e32 v134, v134, v135
	v_mov_b32_e32 v135, v134
	s_nop 1
	v_permlane32_swap_b32 v134, v135
	s_nop 1
	v_add_f32_e32 v134, v134, v135
	v_fmamk_f32 v134, v134, 0x3c800000, v242
	v_rsq_f32_e32 v134, v134
	s_nop 0
	v_pk_mul_f32 v[136:137], v[134:135], v[148:149] op_sel_hi:[0,1]
	v_pk_mul_f32 v[92:93], v[92:93], v[136:137]
	v_pk_mul_f32 v[136:137], v[134:135], v[150:151] op_sel_hi:[0,1]
	v_pk_mul_f32 v[94:95], v[94:95], v[136:137]
	v_pk_mul_f32 v[136:137], v[134:135], v[152:153] op_sel_hi:[0,1]
	v_pk_mul_f32 v[88:89], v[88:89], v[136:137]
	v_pk_mul_f32 v[136:137], v[134:135], v[154:155] op_sel_hi:[0,1]
	v_pk_mul_f32 v[90:91], v[90:91], v[136:137]
	v_pk_mul_f32 v[136:137], v[134:135], v[156:157] op_sel_hi:[0,1]
	v_pk_mul_f32 v[84:85], v[84:85], v[136:137]
	v_pk_mul_f32 v[136:137], v[134:135], v[158:159] op_sel_hi:[0,1]
	v_pk_mul_f32 v[86:87], v[86:87], v[136:137]
	v_pk_mul_f32 v[136:137], v[134:135], v[160:161] op_sel_hi:[0,1]
	v_pk_mul_f32 v[80:81], v[80:81], v[136:137]
	v_pk_mul_f32 v[136:137], v[134:135], v[162:163] op_sel_hi:[0,1]
	v_pk_mul_f32 v[82:83], v[82:83], v[136:137]
	v_pk_mul_f32 v[92:93], v[92:93], s[36:37] op_sel_hi:[1,0]
	v_pk_mul_f32 v[94:95], v[94:95], s[36:37] op_sel_hi:[1,0]
	v_pk_mul_f32 v[88:89], v[88:89], s[36:37] op_sel_hi:[1,0]
	v_pk_mul_f32 v[90:91], v[90:91], s[36:37] op_sel_hi:[1,0]
	v_cvt_pk_bf16_f32 v140, v92, v93
	v_cvt_pk_bf16_f32 v141, v94, v95
	v_cvt_pk_bf16_f32 v142, v88, v89
	v_cvt_pk_bf16_f32 v143, v90, v91
	global_store_dwordx4 v130, v[140:143], s[6:7]
	v_pk_mul_f32 v[84:85], v[84:85], s[36:37] op_sel_hi:[1,0]
	v_pk_mul_f32 v[86:87], v[86:87], s[36:37] op_sel_hi:[1,0]
	v_pk_mul_f32 v[80:81], v[80:81], s[36:37] op_sel_hi:[1,0]
	v_pk_mul_f32 v[82:83], v[82:83], s[36:37] op_sel_hi:[1,0]
	v_cvt_pk_bf16_f32 v144, v84, v85
	v_cvt_pk_bf16_f32 v145, v86, v87
	v_cvt_pk_bf16_f32 v146, v80, v81
	v_cvt_pk_bf16_f32 v147, v82, v83
	global_store_dwordx4 v130, v[144:147], s[6:7] offset:64
	s_add_u32 s6, s6, s33
	s_addc_u32 s7, s7, 0
	v_mul_f32_e32 v134, v77, v77
	v_fmac_f32_e32 v134, v76, v76
	v_fmac_f32_e32 v134, v78, v78
	v_fmac_f32_e32 v134, v79, v79
	v_fmac_f32_e32 v134, v72, v72
	v_fmac_f32_e32 v134, v73, v73
	v_fmac_f32_e32 v134, v74, v74
	v_fmac_f32_e32 v134, v75, v75
	v_fmac_f32_e32 v134, v68, v68
	v_fmac_f32_e32 v134, v69, v69
	v_pk_mul_f32 v[136:137], v[70:71], v[70:71]
	v_pk_mul_f32 v[138:139], v[64:65], v[64:65]
	v_add_f32_e32 v134, v136, v134
	v_add_f32_e32 v134, v137, v134
	v_add_f32_e32 v134, v138, v134
	v_pk_mul_f32 v[136:137], v[66:67], v[66:67]
	v_add_f32_e32 v134, v139, v134
	v_add_f32_e32 v134, v136, v134
	v_add_f32_e32 v134, v137, v134
	ds_swizzle_b32 v135, v134 offset:swizzle(SWAP,16)
	s_waitcnt lgkmcnt(0)
	v_add_f32_e32 v134, v134, v135
	v_mov_b32_e32 v135, v134
	s_nop 1
	v_permlane32_swap_b32 v134, v135
	s_nop 1
	v_add_f32_e32 v134, v134, v135
	v_fmamk_f32 v134, v134, 0x3c800000, v242
	v_rsq_f32_e32 v134, v134
	s_nop 0
	v_pk_mul_f32 v[136:137], v[134:135], v[148:149] op_sel_hi:[0,1]
	v_pk_mul_f32 v[76:77], v[76:77], v[136:137]
	v_pk_mul_f32 v[136:137], v[134:135], v[150:151] op_sel_hi:[0,1]
	v_pk_mul_f32 v[78:79], v[78:79], v[136:137]
	v_pk_mul_f32 v[136:137], v[134:135], v[152:153] op_sel_hi:[0,1]
	v_pk_mul_f32 v[72:73], v[72:73], v[136:137]
	v_pk_mul_f32 v[136:137], v[134:135], v[154:155] op_sel_hi:[0,1]
	v_pk_mul_f32 v[74:75], v[74:75], v[136:137]
	v_pk_mul_f32 v[136:137], v[134:135], v[156:157] op_sel_hi:[0,1]
	v_pk_mul_f32 v[68:69], v[68:69], v[136:137]
	v_pk_mul_f32 v[136:137], v[134:135], v[158:159] op_sel_hi:[0,1]
	v_pk_mul_f32 v[70:71], v[70:71], v[136:137]
	v_pk_mul_f32 v[136:137], v[134:135], v[160:161] op_sel_hi:[0,1]
	v_pk_mul_f32 v[64:65], v[64:65], v[136:137]
	v_pk_mul_f32 v[136:137], v[134:135], v[162:163] op_sel_hi:[0,1]
	v_pk_mul_f32 v[66:67], v[66:67], v[136:137]
	v_pk_mul_f32 v[76:77], v[76:77], s[36:37] op_sel_hi:[1,0]
	v_pk_mul_f32 v[78:79], v[78:79], s[36:37] op_sel_hi:[1,0]
	v_pk_mul_f32 v[72:73], v[72:73], s[36:37] op_sel_hi:[1,0]
	v_pk_mul_f32 v[74:75], v[74:75], s[36:37] op_sel_hi:[1,0]
	v_cvt_pk_bf16_f32 v140, v76, v77
	v_cvt_pk_bf16_f32 v141, v78, v79
	v_cvt_pk_bf16_f32 v142, v72, v73
	v_cvt_pk_bf16_f32 v143, v74, v75
	global_store_dwordx4 v130, v[140:143], s[6:7]
	v_pk_mul_f32 v[68:69], v[68:69], s[36:37] op_sel_hi:[1,0]
	v_pk_mul_f32 v[70:71], v[70:71], s[36:37] op_sel_hi:[1,0]
	v_pk_mul_f32 v[64:65], v[64:65], s[36:37] op_sel_hi:[1,0]
	v_pk_mul_f32 v[66:67], v[66:67], s[36:37] op_sel_hi:[1,0]
	v_cvt_pk_bf16_f32 v144, v68, v69
	v_cvt_pk_bf16_f32 v145, v70, v71
	v_cvt_pk_bf16_f32 v146, v64, v65
	v_cvt_pk_bf16_f32 v147, v66, v67
	global_store_dwordx4 v130, v[144:147], s[6:7] offset:64
	s_add_u32 s6, s6, s34
	s_addc_u32 s7, s7, 0
	v_mul_f32_e32 v134, v61, v61
	v_fmac_f32_e32 v134, v60, v60
	v_fmac_f32_e32 v134, v62, v62
	v_fmac_f32_e32 v134, v63, v63
	v_fmac_f32_e32 v134, v56, v56
	v_fmac_f32_e32 v134, v57, v57
	v_fmac_f32_e32 v134, v58, v58
	v_fmac_f32_e32 v134, v59, v59
	v_fmac_f32_e32 v134, v52, v52
	v_fmac_f32_e32 v134, v53, v53
	v_pk_mul_f32 v[136:137], v[54:55], v[54:55]
	v_pk_mul_f32 v[138:139], v[48:49], v[48:49]
	v_add_f32_e32 v134, v136, v134
	v_add_f32_e32 v134, v137, v134
	v_add_f32_e32 v134, v138, v134
	v_pk_mul_f32 v[136:137], v[50:51], v[50:51]
	v_add_f32_e32 v134, v139, v134
	v_add_f32_e32 v134, v136, v134
	v_add_f32_e32 v134, v137, v134
	ds_swizzle_b32 v135, v134 offset:swizzle(SWAP,16)
	s_waitcnt lgkmcnt(0)
	v_add_f32_e32 v134, v134, v135
	v_mov_b32_e32 v135, v134
	s_nop 1
	v_permlane32_swap_b32 v134, v135
	s_nop 1
	v_add_f32_e32 v134, v134, v135
	v_fmamk_f32 v134, v134, 0x3c800000, v242
	v_rsq_f32_e32 v134, v134
	s_nop 0
	v_pk_mul_f32 v[136:137], v[134:135], v[148:149] op_sel_hi:[0,1]
	v_pk_mul_f32 v[60:61], v[60:61], v[136:137]
	v_pk_mul_f32 v[136:137], v[134:135], v[150:151] op_sel_hi:[0,1]
	v_pk_mul_f32 v[62:63], v[62:63], v[136:137]
	v_pk_mul_f32 v[136:137], v[134:135], v[152:153] op_sel_hi:[0,1]
	v_pk_mul_f32 v[56:57], v[56:57], v[136:137]
	v_pk_mul_f32 v[136:137], v[134:135], v[154:155] op_sel_hi:[0,1]
	v_pk_mul_f32 v[58:59], v[58:59], v[136:137]
	v_pk_mul_f32 v[136:137], v[134:135], v[156:157] op_sel_hi:[0,1]
	v_pk_mul_f32 v[52:53], v[52:53], v[136:137]
	v_pk_mul_f32 v[136:137], v[134:135], v[158:159] op_sel_hi:[0,1]
	v_pk_mul_f32 v[54:55], v[54:55], v[136:137]
	v_pk_mul_f32 v[136:137], v[134:135], v[160:161] op_sel_hi:[0,1]
	v_pk_mul_f32 v[48:49], v[48:49], v[136:137]
	v_pk_mul_f32 v[136:137], v[134:135], v[162:163] op_sel_hi:[0,1]
	v_pk_mul_f32 v[50:51], v[50:51], v[136:137]
	v_pk_mul_f32 v[60:61], v[60:61], s[36:37] op_sel_hi:[1,0]
	v_pk_mul_f32 v[62:63], v[62:63], s[36:37] op_sel_hi:[1,0]
	v_pk_mul_f32 v[56:57], v[56:57], s[36:37] op_sel_hi:[1,0]
	v_pk_mul_f32 v[58:59], v[58:59], s[36:37] op_sel_hi:[1,0]
	v_cvt_pk_bf16_f32 v140, v60, v61
	v_cvt_pk_bf16_f32 v141, v62, v63
	v_cvt_pk_bf16_f32 v142, v56, v57
	v_cvt_pk_bf16_f32 v143, v58, v59
	global_store_dwordx4 v130, v[140:143], s[6:7]
	v_pk_mul_f32 v[52:53], v[52:53], s[36:37] op_sel_hi:[1,0]
	v_pk_mul_f32 v[54:55], v[54:55], s[36:37] op_sel_hi:[1,0]
	v_pk_mul_f32 v[48:49], v[48:49], s[36:37] op_sel_hi:[1,0]
	v_pk_mul_f32 v[50:51], v[50:51], s[36:37] op_sel_hi:[1,0]
	v_cvt_pk_bf16_f32 v144, v52, v53
	v_cvt_pk_bf16_f32 v145, v54, v55
	v_cvt_pk_bf16_f32 v146, v48, v49
	v_cvt_pk_bf16_f32 v147, v50, v51
	global_store_dwordx4 v130, v[144:147], s[6:7] offset:64
	s_add_u32 s6, s6, s33
	s_addc_u32 s7, s7, 0
	v_mul_f32_e32 v134, v45, v45
	v_fmac_f32_e32 v134, v44, v44
	v_fmac_f32_e32 v134, v46, v46
	v_fmac_f32_e32 v134, v47, v47
	v_fmac_f32_e32 v134, v40, v40
	v_fmac_f32_e32 v134, v41, v41
	v_fmac_f32_e32 v134, v42, v42
	v_fmac_f32_e32 v134, v43, v43
	v_fmac_f32_e32 v134, v36, v36
	v_fmac_f32_e32 v134, v37, v37
	v_pk_mul_f32 v[136:137], v[38:39], v[38:39]
	v_pk_mul_f32 v[138:139], v[32:33], v[32:33]
	v_add_f32_e32 v134, v136, v134
	v_add_f32_e32 v134, v137, v134
	v_add_f32_e32 v134, v138, v134
	v_pk_mul_f32 v[136:137], v[34:35], v[34:35]
	v_add_f32_e32 v134, v139, v134
	v_add_f32_e32 v134, v136, v134
	v_add_f32_e32 v134, v137, v134
	ds_swizzle_b32 v135, v134 offset:swizzle(SWAP,16)
	s_waitcnt lgkmcnt(0)
	v_add_f32_e32 v134, v134, v135
	v_mov_b32_e32 v135, v134
	s_nop 1
	v_permlane32_swap_b32 v134, v135
	s_nop 1
	v_add_f32_e32 v134, v134, v135
	v_fmamk_f32 v134, v134, 0x3c800000, v242
	v_rsq_f32_e32 v134, v134
	s_nop 0
	v_pk_mul_f32 v[136:137], v[134:135], v[148:149] op_sel_hi:[0,1]
	v_pk_mul_f32 v[44:45], v[44:45], v[136:137]
	v_pk_mul_f32 v[136:137], v[134:135], v[150:151] op_sel_hi:[0,1]
	v_pk_mul_f32 v[46:47], v[46:47], v[136:137]
	v_pk_mul_f32 v[136:137], v[134:135], v[152:153] op_sel_hi:[0,1]
	v_pk_mul_f32 v[40:41], v[40:41], v[136:137]
	v_pk_mul_f32 v[136:137], v[134:135], v[154:155] op_sel_hi:[0,1]
	v_pk_mul_f32 v[42:43], v[42:43], v[136:137]
	v_pk_mul_f32 v[136:137], v[134:135], v[156:157] op_sel_hi:[0,1]
	v_pk_mul_f32 v[36:37], v[36:37], v[136:137]
	v_pk_mul_f32 v[136:137], v[134:135], v[158:159] op_sel_hi:[0,1]
	v_pk_mul_f32 v[38:39], v[38:39], v[136:137]
	v_pk_mul_f32 v[136:137], v[134:135], v[160:161] op_sel_hi:[0,1]
	v_pk_mul_f32 v[32:33], v[32:33], v[136:137]
	v_pk_mul_f32 v[136:137], v[134:135], v[162:163] op_sel_hi:[0,1]
	v_pk_mul_f32 v[34:35], v[34:35], v[136:137]
	v_pk_mul_f32 v[44:45], v[44:45], s[36:37] op_sel_hi:[1,0]
	v_pk_mul_f32 v[46:47], v[46:47], s[36:37] op_sel_hi:[1,0]
	v_pk_mul_f32 v[40:41], v[40:41], s[36:37] op_sel_hi:[1,0]
	v_pk_mul_f32 v[42:43], v[42:43], s[36:37] op_sel_hi:[1,0]
	v_cvt_pk_bf16_f32 v140, v44, v45
	v_cvt_pk_bf16_f32 v141, v46, v47
	v_cvt_pk_bf16_f32 v142, v40, v41
	v_cvt_pk_bf16_f32 v143, v42, v43
	global_store_dwordx4 v130, v[140:143], s[6:7]
	v_pk_mul_f32 v[36:37], v[36:37], s[36:37] op_sel_hi:[1,0]
	v_pk_mul_f32 v[38:39], v[38:39], s[36:37] op_sel_hi:[1,0]
	v_pk_mul_f32 v[32:33], v[32:33], s[36:37] op_sel_hi:[1,0]
	v_pk_mul_f32 v[34:35], v[34:35], s[36:37] op_sel_hi:[1,0]
	v_cvt_pk_bf16_f32 v144, v36, v37
	v_cvt_pk_bf16_f32 v145, v38, v39
	v_cvt_pk_bf16_f32 v146, v32, v33
	v_cvt_pk_bf16_f32 v147, v34, v35
	global_store_dwordx4 v130, v[144:147], s[6:7] offset:64
	s_add_u32 s6, s6, s33
	s_addc_u32 s7, s7, 0
	v_mul_f32_e32 v134, v29, v29
	v_fmac_f32_e32 v134, v28, v28
	v_fmac_f32_e32 v134, v30, v30
	v_fmac_f32_e32 v134, v31, v31
	v_fmac_f32_e32 v134, v24, v24
	v_fmac_f32_e32 v134, v25, v25
	v_fmac_f32_e32 v134, v26, v26
	v_fmac_f32_e32 v134, v27, v27
	v_fmac_f32_e32 v134, v20, v20
	v_fmac_f32_e32 v134, v21, v21
	v_pk_mul_f32 v[136:137], v[22:23], v[22:23]
	v_pk_mul_f32 v[138:139], v[16:17], v[16:17]
	v_add_f32_e32 v134, v136, v134
	v_add_f32_e32 v134, v137, v134
	v_add_f32_e32 v134, v138, v134
	v_pk_mul_f32 v[136:137], v[18:19], v[18:19]
	v_add_f32_e32 v134, v139, v134
	v_add_f32_e32 v134, v136, v134
	v_add_f32_e32 v134, v137, v134
	ds_swizzle_b32 v135, v134 offset:swizzle(SWAP,16)
	s_waitcnt lgkmcnt(0)
	v_add_f32_e32 v134, v134, v135
	v_mov_b32_e32 v135, v134
	s_nop 1
	v_permlane32_swap_b32 v134, v135
	s_nop 1
	v_add_f32_e32 v134, v134, v135
	v_fmamk_f32 v134, v134, 0x3c800000, v242
	v_rsq_f32_e32 v134, v134
	s_nop 0
	v_pk_mul_f32 v[136:137], v[134:135], v[148:149] op_sel_hi:[0,1]
	v_pk_mul_f32 v[28:29], v[28:29], v[136:137]
	v_pk_mul_f32 v[136:137], v[134:135], v[150:151] op_sel_hi:[0,1]
	v_pk_mul_f32 v[30:31], v[30:31], v[136:137]
	v_pk_mul_f32 v[136:137], v[134:135], v[152:153] op_sel_hi:[0,1]
	v_pk_mul_f32 v[24:25], v[24:25], v[136:137]
	v_pk_mul_f32 v[136:137], v[134:135], v[154:155] op_sel_hi:[0,1]
	v_pk_mul_f32 v[26:27], v[26:27], v[136:137]
	v_pk_mul_f32 v[136:137], v[134:135], v[156:157] op_sel_hi:[0,1]
	v_pk_mul_f32 v[20:21], v[20:21], v[136:137]
	v_pk_mul_f32 v[136:137], v[134:135], v[158:159] op_sel_hi:[0,1]
	v_pk_mul_f32 v[22:23], v[22:23], v[136:137]
	v_pk_mul_f32 v[136:137], v[134:135], v[160:161] op_sel_hi:[0,1]
	v_pk_mul_f32 v[16:17], v[16:17], v[136:137]
	v_pk_mul_f32 v[136:137], v[134:135], v[162:163] op_sel_hi:[0,1]
	v_pk_mul_f32 v[18:19], v[18:19], v[136:137]
	v_pk_mul_f32 v[28:29], v[28:29], s[36:37] op_sel_hi:[1,0]
	v_pk_mul_f32 v[30:31], v[30:31], s[36:37] op_sel_hi:[1,0]
	v_pk_mul_f32 v[24:25], v[24:25], s[36:37] op_sel_hi:[1,0]
	v_pk_mul_f32 v[26:27], v[26:27], s[36:37] op_sel_hi:[1,0]
	v_cvt_pk_bf16_f32 v140, v28, v29
	v_cvt_pk_bf16_f32 v141, v30, v31
	v_cvt_pk_bf16_f32 v142, v24, v25
	v_cvt_pk_bf16_f32 v143, v26, v27
	global_store_dwordx4 v130, v[140:143], s[6:7]
	v_pk_mul_f32 v[20:21], v[20:21], s[36:37] op_sel_hi:[1,0]
	v_pk_mul_f32 v[22:23], v[22:23], s[36:37] op_sel_hi:[1,0]
	v_pk_mul_f32 v[16:17], v[16:17], s[36:37] op_sel_hi:[1,0]
	v_pk_mul_f32 v[18:19], v[18:19], s[36:37] op_sel_hi:[1,0]
	v_cvt_pk_bf16_f32 v144, v20, v21
	v_cvt_pk_bf16_f32 v145, v22, v23
	v_cvt_pk_bf16_f32 v146, v16, v17
	v_cvt_pk_bf16_f32 v147, v18, v19
	global_store_dwordx4 v130, v[144:147], s[6:7] offset:64
	s_add_u32 s6, s6, s33
	s_addc_u32 s7, s7, 0
	v_mul_f32_e32 v134, v13, v13
	v_fmac_f32_e32 v134, v12, v12
	v_fmac_f32_e32 v134, v14, v14
	v_fmac_f32_e32 v134, v15, v15
	v_fmac_f32_e32 v134, v4, v4
	v_fmac_f32_e32 v134, v5, v5
	v_fmac_f32_e32 v134, v6, v6
	v_fmac_f32_e32 v134, v7, v7
	v_fmac_f32_e32 v134, v8, v8
	v_fmac_f32_e32 v134, v9, v9
	v_pk_mul_f32 v[136:137], v[10:11], v[10:11]
	v_pk_mul_f32 v[138:139], v[0:1], v[0:1]
	v_add_f32_e32 v134, v136, v134
	v_add_f32_e32 v134, v137, v134
	v_add_f32_e32 v134, v138, v134
	v_pk_mul_f32 v[136:137], v[2:3], v[2:3]
	v_add_f32_e32 v134, v139, v134
	v_add_f32_e32 v134, v136, v134
	v_add_f32_e32 v134, v137, v134
	ds_swizzle_b32 v135, v134 offset:swizzle(SWAP,16)
	s_waitcnt lgkmcnt(0)
	v_add_f32_e32 v134, v134, v135
	v_mov_b32_e32 v135, v134
	s_nop 1
	v_permlane32_swap_b32 v134, v135
	s_nop 1
	v_add_f32_e32 v134, v134, v135
	v_fmamk_f32 v134, v134, 0x3c800000, v242
	v_rsq_f32_e32 v134, v134
	s_nop 0
	v_pk_mul_f32 v[136:137], v[134:135], v[148:149] op_sel_hi:[0,1]
	v_pk_mul_f32 v[12:13], v[12:13], v[136:137]
	v_pk_mul_f32 v[136:137], v[134:135], v[150:151] op_sel_hi:[0,1]
	v_pk_mul_f32 v[14:15], v[14:15], v[136:137]
	v_pk_mul_f32 v[136:137], v[134:135], v[152:153] op_sel_hi:[0,1]
	v_pk_mul_f32 v[4:5], v[4:5], v[136:137]
	v_pk_mul_f32 v[136:137], v[134:135], v[154:155] op_sel_hi:[0,1]
	v_pk_mul_f32 v[6:7], v[6:7], v[136:137]
	v_pk_mul_f32 v[136:137], v[134:135], v[156:157] op_sel_hi:[0,1]
	v_pk_mul_f32 v[8:9], v[8:9], v[136:137]
	v_pk_mul_f32 v[136:137], v[134:135], v[158:159] op_sel_hi:[0,1]
	v_pk_mul_f32 v[10:11], v[10:11], v[136:137]
	v_pk_mul_f32 v[136:137], v[134:135], v[160:161] op_sel_hi:[0,1]
	v_pk_mul_f32 v[0:1], v[0:1], v[136:137]
	v_pk_mul_f32 v[136:137], v[134:135], v[162:163] op_sel_hi:[0,1]
	v_pk_mul_f32 v[2:3], v[2:3], v[136:137]
	v_pk_mul_f32 v[12:13], v[12:13], s[36:37] op_sel_hi:[1,0]
	v_pk_mul_f32 v[14:15], v[14:15], s[36:37] op_sel_hi:[1,0]
	v_pk_mul_f32 v[4:5], v[4:5], s[36:37] op_sel_hi:[1,0]
	v_pk_mul_f32 v[6:7], v[6:7], s[36:37] op_sel_hi:[1,0]
	v_cvt_pk_bf16_f32 v140, v12, v13
	v_cvt_pk_bf16_f32 v141, v14, v15
	v_cvt_pk_bf16_f32 v142, v4, v5
	v_cvt_pk_bf16_f32 v143, v6, v7
	global_store_dwordx4 v130, v[140:143], s[6:7]
	v_pk_mul_f32 v[8:9], v[8:9], s[36:37] op_sel_hi:[1,0]
	v_pk_mul_f32 v[10:11], v[10:11], s[36:37] op_sel_hi:[1,0]
	v_pk_mul_f32 v[0:1], v[0:1], s[36:37] op_sel_hi:[1,0]
	v_pk_mul_f32 v[2:3], v[2:3], s[36:37] op_sel_hi:[1,0]
	v_cvt_pk_bf16_f32 v144, v8, v9
	v_cvt_pk_bf16_f32 v145, v10, v11
	v_cvt_pk_bf16_f32 v146, v0, v1
	v_cvt_pk_bf16_f32 v147, v2, v3
	global_store_dwordx4 v130, v[144:147], s[6:7] offset:64
	s_branch .LBB0_638
.Lq3_C:
	global_load_dwordx4 v[164:167], v131, s[8:9]
	global_load_dwordx4 v[168:171], v132, s[8:9]
	global_load_dwordx4 v[172:175], v131, s[8:9] offset:64
	global_load_dwordx4 v[176:179], v132, s[8:9] offset:64
	s_add_u32 s8, s8, 0x800
	s_addc_u32 s9, s9, 0
	global_load_dwordx4 v[202:205], v131, s[8:9]
	global_load_dwordx4 v[206:209], v132, s[8:9]
	global_load_dwordx4 v[210:213], v131, s[8:9] offset:64
	global_load_dwordx4 v[214:217], v132, s[8:9] offset:64
	s_waitcnt vmcnt(4)
	v_pk_mul_f32 v[136:137], v[126:127], v[168:169] op_sel:[1,0] op_sel_hi:[0,0]
	v_pk_fma_f32 v[126:127], v[126:127], v[164:165], v[136:137] op_sel:[0,0,0] op_sel_hi:[1,0,1] neg_lo:[0,0,1]
	v_pk_mul_f32 v[136:137], v[128:129], v[168:169] op_sel:[1,1] op_sel_hi:[0,1]
	v_pk_fma_f32 v[128:129], v[128:129], v[164:165], v[136:137] op_sel:[0,1,0] op_sel_hi:[1,1,1] neg_lo:[0,0,1]
	v_pk_mul_f32 v[136:137], v[122:123], v[170:171] op_sel:[1,0] op_sel_hi:[0,0]
	v_pk_fma_f32 v[122:123], v[122:123], v[166:167], v[136:137] op_sel:[0,0,0] op_sel_hi:[1,0,1] neg_lo:[0,0,1]
	v_pk_mul_f32 v[136:137], v[124:125], v[170:171] op_sel:[1,1] op_sel_hi:[0,1]
	v_pk_fma_f32 v[124:125], v[124:125], v[166:167], v[136:137] op_sel:[0,1,0] op_sel_hi:[1,1,1] neg_lo:[0,0,1]
	v_pk_mul_f32 v[126:127], v[126:127], s[36:37] op_sel_hi:[1,0]
	v_pk_mul_f32 v[128:129], v[128:129], s[36:37] op_sel_hi:[1,0]
	v_pk_mul_f32 v[122:123], v[122:123], s[36:37] op_sel_hi:[1,0]
	v_pk_mul_f32 v[124:125], v[124:125], s[36:37] op_sel_hi:[1,0]
	v_cvt_pk_bf16_f32 v140, v126, v127
	v_cvt_pk_bf16_f32 v141, v128, v129
	v_cvt_pk_bf16_f32 v142, v122, v123
	v_cvt_pk_bf16_f32 v143, v124, v125
	global_store_dwordx4 v130, v[140:143], s[6:7]
	v_pk_mul_f32 v[136:137], v[118:119], v[176:177] op_sel:[1,0] op_sel_hi:[0,0]
	v_pk_fma_f32 v[118:119], v[118:119], v[172:173], v[136:137] op_sel:[0,0,0] op_sel_hi:[1,0,1] neg_lo:[0,0,1]
	v_pk_mul_f32 v[136:137], v[120:121], v[176:177] op_sel:[1,1] op_sel_hi:[0,1]
	v_pk_fma_f32 v[120:121], v[120:121], v[172:173], v[136:137] op_sel:[0,1,0] op_sel_hi:[1,1,1] neg_lo:[0,0,1]
	v_pk_mul_f32 v[136:137], v[114:115], v[178:179] op_sel:[1,0] op_sel_hi:[0,0]
	v_pk_fma_f32 v[114:115], v[114:115], v[174:175], v[136:137] op_sel:[0,0,0] op_sel_hi:[1,0,1] neg_lo:[0,0,1]
	v_pk_mul_f32 v[136:137], v[116:117], v[178:179] op_sel:[1,1] op_sel_hi:[0,1]
	v_pk_fma_f32 v[116:117], v[116:117], v[174:175], v[136:137] op_sel:[0,1,0] op_sel_hi:[1,1,1] neg_lo:[0,0,1]
	v_pk_mul_f32 v[118:119], v[118:119], s[36:37] op_sel_hi:[1,0]
	v_pk_mul_f32 v[120:121], v[120:121], s[36:37] op_sel_hi:[1,0]
	v_pk_mul_f32 v[114:115], v[114:115], s[36:37] op_sel_hi:[1,0]
	v_pk_mul_f32 v[116:117], v[116:117], s[36:37] op_sel_hi:[1,0]
	v_cvt_pk_bf16_f32 v144, v118, v119
	v_cvt_pk_bf16_f32 v145, v120, v121
	v_cvt_pk_bf16_f32 v146, v114, v115
	v_cvt_pk_bf16_f32 v147, v116, v117
	global_store_dwordx4 v130, v[144:147], s[6:7] offset:64
	s_add_u32 s6, s6, s33
	s_addc_u32 s7, s7, 0
	s_add_u32 s8, s8, 0x800
	s_addc_u32 s9, s9, 0
	global_load_dwordx4 v[164:167], v131, s[8:9]
	global_load_dwordx4 v[168:171], v132, s[8:9]
	global_load_dwordx4 v[172:175], v131, s[8:9] offset:64
	global_load_dwordx4 v[176:179], v132, s[8:9] offset:64
	s_waitcnt vmcnt(6)
	v_pk_mul_f32 v[136:137], v[108:109], v[206:207] op_sel:[1,0] op_sel_hi:[0,0]
	v_pk_fma_f32 v[108:109], v[108:109], v[202:203], v[136:137] op_sel:[0,0,0] op_sel_hi:[1,0,1] neg_lo:[0,0,1]
	v_pk_mul_f32 v[136:137], v[110:111], v[206:207] op_sel:[1,1] op_sel_hi:[0,1]
	v_pk_fma_f32 v[110:111], v[110:111], v[202:203], v[136:137] op_sel:[0,1,0] op_sel_hi:[1,1,1] neg_lo:[0,0,1]
	v_pk_mul_f32 v[136:137], v[104:105], v[208:209] op_sel:[1,0] op_sel_hi:[0,0]
	v_pk_fma_f32 v[104:105], v[104:105], v[204:205], v[136:137] op_sel:[0,0,0] op_sel_hi:[1,0,1] neg_lo:[0,0,1]
	v_pk_mul_f32 v[136:137], v[106:107], v[208:209] op_sel:[1,1] op_sel_hi:[0,1]
	v_pk_fma_f32 v[106:107], v[106:107], v[204:205], v[136:137] op_sel:[0,1,0] op_sel_hi:[1,1,1] neg_lo:[0,0,1]
	v_pk_mul_f32 v[108:109], v[108:109], s[36:37] op_sel_hi:[1,0]
	v_pk_mul_f32 v[110:111], v[110:111], s[36:37] op_sel_hi:[1,0]
	v_pk_mul_f32 v[104:105], v[104:105], s[36:37] op_sel_hi:[1,0]
	v_pk_mul_f32 v[106:107], v[106:107], s[36:37] op_sel_hi:[1,0]
	v_cvt_pk_bf16_f32 v140, v108, v109
	v_cvt_pk_bf16_f32 v141, v110, v111
	v_cvt_pk_bf16_f32 v142, v104, v105
	v_cvt_pk_bf16_f32 v143, v106, v107
	global_store_dwordx4 v130, v[140:143], s[6:7]
	v_pk_mul_f32 v[136:137], v[100:101], v[214:215] op_sel:[1,0] op_sel_hi:[0,0]
	v_pk_fma_f32 v[100:101], v[100:101], v[210:211], v[136:137] op_sel:[0,0,0] op_sel_hi:[1,0,1] neg_lo:[0,0,1]
	v_pk_mul_f32 v[136:137], v[102:103], v[214:215] op_sel:[1,1] op_sel_hi:[0,1]
	v_pk_fma_f32 v[102:103], v[102:103], v[210:211], v[136:137] op_sel:[0,1,0] op_sel_hi:[1,1,1] neg_lo:[0,0,1]
	v_pk_mul_f32 v[136:137], v[96:97], v[216:217] op_sel:[1,0] op_sel_hi:[0,0]
	v_pk_fma_f32 v[96:97], v[96:97], v[212:213], v[136:137] op_sel:[0,0,0] op_sel_hi:[1,0,1] neg_lo:[0,0,1]
	v_pk_mul_f32 v[136:137], v[98:99], v[216:217] op_sel:[1,1] op_sel_hi:[0,1]
	v_pk_fma_f32 v[98:99], v[98:99], v[212:213], v[136:137] op_sel:[0,1,0] op_sel_hi:[1,1,1] neg_lo:[0,0,1]
	v_pk_mul_f32 v[100:101], v[100:101], s[36:37] op_sel_hi:[1,0]
	v_pk_mul_f32 v[102:103], v[102:103], s[36:37] op_sel_hi:[1,0]
	v_pk_mul_f32 v[96:97], v[96:97], s[36:37] op_sel_hi:[1,0]
	v_pk_mul_f32 v[98:99], v[98:99], s[36:37] op_sel_hi:[1,0]
	v_cvt_pk_bf16_f32 v144, v100, v101
	v_cvt_pk_bf16_f32 v145, v102, v103
	v_cvt_pk_bf16_f32 v146, v96, v97
	v_cvt_pk_bf16_f32 v147, v98, v99
	global_store_dwordx4 v130, v[144:147], s[6:7] offset:64
	s_add_u32 s6, s6, s33
	s_addc_u32 s7, s7, 0
	s_add_u32 s8, s8, 0x800
	s_addc_u32 s9, s9, 0
	global_load_dwordx4 v[202:205], v131, s[8:9]
	global_load_dwordx4 v[206:209], v132, s[8:9]
	global_load_dwordx4 v[210:213], v131, s[8:9] offset:64
	global_load_dwordx4 v[214:217], v132, s[8:9] offset:64
	s_waitcnt vmcnt(6)
	v_pk_mul_f32 v[136:137], v[92:93], v[168:169] op_sel:[1,0] op_sel_hi:[0,0]
	v_pk_fma_f32 v[92:93], v[92:93], v[164:165], v[136:137] op_sel:[0,0,0] op_sel_hi:[1,0,1] neg_lo:[0,0,1]
	v_pk_mul_f32 v[136:137], v[94:95], v[168:169] op_sel:[1,1] op_sel_hi:[0,1]
	v_pk_fma_f32 v[94:95], v[94:95], v[164:165], v[136:137] op_sel:[0,1,0] op_sel_hi:[1,1,1] neg_lo:[0,0,1]
	v_pk_mul_f32 v[136:137], v[88:89], v[170:171] op_sel:[1,0] op_sel_hi:[0,0]
	v_pk_fma_f32 v[88:89], v[88:89], v[166:167], v[136:137] op_sel:[0,0,0] op_sel_hi:[1,0,1] neg_lo:[0,0,1]
	v_pk_mul_f32 v[136:137], v[90:91], v[170:171] op_sel:[1,1] op_sel_hi:[0,1]
	v_pk_fma_f32 v[90:91], v[90:91], v[166:167], v[136:137] op_sel:[0,1,0] op_sel_hi:[1,1,1] neg_lo:[0,0,1]
	v_pk_mul_f32 v[92:93], v[92:93], s[36:37] op_sel_hi:[1,0]
	v_pk_mul_f32 v[94:95], v[94:95], s[36:37] op_sel_hi:[1,0]
	v_pk_mul_f32 v[88:89], v[88:89], s[36:37] op_sel_hi:[1,0]
	v_pk_mul_f32 v[90:91], v[90:91], s[36:37] op_sel_hi:[1,0]
	v_cvt_pk_bf16_f32 v140, v92, v93
	v_cvt_pk_bf16_f32 v141, v94, v95
	v_cvt_pk_bf16_f32 v142, v88, v89
	v_cvt_pk_bf16_f32 v143, v90, v91
	global_store_dwordx4 v130, v[140:143], s[6:7]
	v_pk_mul_f32 v[136:137], v[84:85], v[176:177] op_sel:[1,0] op_sel_hi:[0,0]
	v_pk_fma_f32 v[84:85], v[84:85], v[172:173], v[136:137] op_sel:[0,0,0] op_sel_hi:[1,0,1] neg_lo:[0,0,1]
	v_pk_mul_f32 v[136:137], v[86:87], v[176:177] op_sel:[1,1] op_sel_hi:[0,1]
	v_pk_fma_f32 v[86:87], v[86:87], v[172:173], v[136:137] op_sel:[0,1,0] op_sel_hi:[1,1,1] neg_lo:[0,0,1]
	v_pk_mul_f32 v[136:137], v[80:81], v[178:179] op_sel:[1,0] op_sel_hi:[0,0]
	v_pk_fma_f32 v[80:81], v[80:81], v[174:175], v[136:137] op_sel:[0,0,0] op_sel_hi:[1,0,1] neg_lo:[0,0,1]
	v_pk_mul_f32 v[136:137], v[82:83], v[178:179] op_sel:[1,1] op_sel_hi:[0,1]
	v_pk_fma_f32 v[82:83], v[82:83], v[174:175], v[136:137] op_sel:[0,1,0] op_sel_hi:[1,1,1] neg_lo:[0,0,1]
	v_pk_mul_f32 v[84:85], v[84:85], s[36:37] op_sel_hi:[1,0]
	v_pk_mul_f32 v[86:87], v[86:87], s[36:37] op_sel_hi:[1,0]
	v_pk_mul_f32 v[80:81], v[80:81], s[36:37] op_sel_hi:[1,0]
	v_pk_mul_f32 v[82:83], v[82:83], s[36:37] op_sel_hi:[1,0]
	v_cvt_pk_bf16_f32 v144, v84, v85
	v_cvt_pk_bf16_f32 v145, v86, v87
	v_cvt_pk_bf16_f32 v146, v80, v81
	v_cvt_pk_bf16_f32 v147, v82, v83
	global_store_dwordx4 v130, v[144:147], s[6:7] offset:64
	s_add_u32 s6, s6, s33
	s_addc_u32 s7, s7, 0
	s_add_u32 s8, s8, 0x2800
	s_addc_u32 s9, s9, 0
	global_load_dwordx4 v[164:167], v131, s[8:9]
	global_load_dwordx4 v[168:171], v132, s[8:9]
	global_load_dwordx4 v[172:175], v131, s[8:9] offset:64
	global_load_dwordx4 v[176:179], v132, s[8:9] offset:64
	s_waitcnt vmcnt(6)
	v_pk_mul_f32 v[136:137], v[76:77], v[206:207] op_sel:[1,0] op_sel_hi:[0,0]
	v_pk_fma_f32 v[76:77], v[76:77], v[202:203], v[136:137] op_sel:[0,0,0] op_sel_hi:[1,0,1] neg_lo:[0,0,1]
	v_pk_mul_f32 v[136:137], v[78:79], v[206:207] op_sel:[1,1] op_sel_hi:[0,1]
	v_pk_fma_f32 v[78:79], v[78:79], v[202:203], v[136:137] op_sel:[0,1,0] op_sel_hi:[1,1,1] neg_lo:[0,0,1]
	v_pk_mul_f32 v[136:137], v[72:73], v[208:209] op_sel:[1,0] op_sel_hi:[0,0]
	v_pk_fma_f32 v[72:73], v[72:73], v[204:205], v[136:137] op_sel:[0,0,0] op_sel_hi:[1,0,1] neg_lo:[0,0,1]
	v_pk_mul_f32 v[136:137], v[74:75], v[208:209] op_sel:[1,1] op_sel_hi:[0,1]
	v_pk_fma_f32 v[74:75], v[74:75], v[204:205], v[136:137] op_sel:[0,1,0] op_sel_hi:[1,1,1] neg_lo:[0,0,1]
	v_pk_mul_f32 v[76:77], v[76:77], s[36:37] op_sel_hi:[1,0]
	v_pk_mul_f32 v[78:79], v[78:79], s[36:37] op_sel_hi:[1,0]
	v_pk_mul_f32 v[72:73], v[72:73], s[36:37] op_sel_hi:[1,0]
	v_pk_mul_f32 v[74:75], v[74:75], s[36:37] op_sel_hi:[1,0]
	v_cvt_pk_bf16_f32 v140, v76, v77
	v_cvt_pk_bf16_f32 v141, v78, v79
	v_cvt_pk_bf16_f32 v142, v72, v73
	v_cvt_pk_bf16_f32 v143, v74, v75
	global_store_dwordx4 v130, v[140:143], s[6:7]
	v_pk_mul_f32 v[136:137], v[68:69], v[214:215] op_sel:[1,0] op_sel_hi:[0,0]
	v_pk_fma_f32 v[68:69], v[68:69], v[210:211], v[136:137] op_sel:[0,0,0] op_sel_hi:[1,0,1] neg_lo:[0,0,1]
	v_pk_mul_f32 v[136:137], v[70:71], v[214:215] op_sel:[1,1] op_sel_hi:[0,1]
	v_pk_fma_f32 v[70:71], v[70:71], v[210:211], v[136:137] op_sel:[0,1,0] op_sel_hi:[1,1,1] neg_lo:[0,0,1]
	v_pk_mul_f32 v[136:137], v[64:65], v[216:217] op_sel:[1,0] op_sel_hi:[0,0]
	v_pk_fma_f32 v[64:65], v[64:65], v[212:213], v[136:137] op_sel:[0,0,0] op_sel_hi:[1,0,1] neg_lo:[0,0,1]
	v_pk_mul_f32 v[136:137], v[66:67], v[216:217] op_sel:[1,1] op_sel_hi:[0,1]
	v_pk_fma_f32 v[66:67], v[66:67], v[212:213], v[136:137] op_sel:[0,1,0] op_sel_hi:[1,1,1] neg_lo:[0,0,1]
	v_pk_mul_f32 v[68:69], v[68:69], s[36:37] op_sel_hi:[1,0]
	v_pk_mul_f32 v[70:71], v[70:71], s[36:37] op_sel_hi:[1,0]
	v_pk_mul_f32 v[64:65], v[64:65], s[36:37] op_sel_hi:[1,0]
	v_pk_mul_f32 v[66:67], v[66:67], s[36:37] op_sel_hi:[1,0]
	v_cvt_pk_bf16_f32 v144, v68, v69
	v_cvt_pk_bf16_f32 v145, v70, v71
	v_cvt_pk_bf16_f32 v146, v64, v65
	v_cvt_pk_bf16_f32 v147, v66, v67
	global_store_dwordx4 v130, v[144:147], s[6:7] offset:64
	s_add_u32 s6, s6, s34
	s_addc_u32 s7, s7, 0
	s_add_u32 s8, s8, 0x800
	s_addc_u32 s9, s9, 0
	global_load_dwordx4 v[202:205], v131, s[8:9]
	global_load_dwordx4 v[206:209], v132, s[8:9]
	global_load_dwordx4 v[210:213], v131, s[8:9] offset:64
	global_load_dwordx4 v[214:217], v132, s[8:9] offset:64
	s_waitcnt vmcnt(6)
	v_pk_mul_f32 v[136:137], v[60:61], v[168:169] op_sel:[1,0] op_sel_hi:[0,0]
	v_pk_fma_f32 v[60:61], v[60:61], v[164:165], v[136:137] op_sel:[0,0,0] op_sel_hi:[1,0,1] neg_lo:[0,0,1]
	v_pk_mul_f32 v[136:137], v[62:63], v[168:169] op_sel:[1,1] op_sel_hi:[0,1]
	v_pk_fma_f32 v[62:63], v[62:63], v[164:165], v[136:137] op_sel:[0,1,0] op_sel_hi:[1,1,1] neg_lo:[0,0,1]
	v_pk_mul_f32 v[136:137], v[56:57], v[170:171] op_sel:[1,0] op_sel_hi:[0,0]
	v_pk_fma_f32 v[56:57], v[56:57], v[166:167], v[136:137] op_sel:[0,0,0] op_sel_hi:[1,0,1] neg_lo:[0,0,1]
	v_pk_mul_f32 v[136:137], v[58:59], v[170:171] op_sel:[1,1] op_sel_hi:[0,1]
	v_pk_fma_f32 v[58:59], v[58:59], v[166:167], v[136:137] op_sel:[0,1,0] op_sel_hi:[1,1,1] neg_lo:[0,0,1]
	v_pk_mul_f32 v[60:61], v[60:61], s[36:37] op_sel_hi:[1,0]
	v_pk_mul_f32 v[62:63], v[62:63], s[36:37] op_sel_hi:[1,0]
	v_pk_mul_f32 v[56:57], v[56:57], s[36:37] op_sel_hi:[1,0]
	v_pk_mul_f32 v[58:59], v[58:59], s[36:37] op_sel_hi:[1,0]
	v_cvt_pk_bf16_f32 v140, v60, v61
	v_cvt_pk_bf16_f32 v141, v62, v63
	v_cvt_pk_bf16_f32 v142, v56, v57
	v_cvt_pk_bf16_f32 v143, v58, v59
	global_store_dwordx4 v130, v[140:143], s[6:7]
	v_pk_mul_f32 v[136:137], v[52:53], v[176:177] op_sel:[1,0] op_sel_hi:[0,0]
	v_pk_fma_f32 v[52:53], v[52:53], v[172:173], v[136:137] op_sel:[0,0,0] op_sel_hi:[1,0,1] neg_lo:[0,0,1]
	v_pk_mul_f32 v[136:137], v[54:55], v[176:177] op_sel:[1,1] op_sel_hi:[0,1]
	v_pk_fma_f32 v[54:55], v[54:55], v[172:173], v[136:137] op_sel:[0,1,0] op_sel_hi:[1,1,1] neg_lo:[0,0,1]
	v_pk_mul_f32 v[136:137], v[48:49], v[178:179] op_sel:[1,0] op_sel_hi:[0,0]
	v_pk_fma_f32 v[48:49], v[48:49], v[174:175], v[136:137] op_sel:[0,0,0] op_sel_hi:[1,0,1] neg_lo:[0,0,1]
	v_pk_mul_f32 v[136:137], v[50:51], v[178:179] op_sel:[1,1] op_sel_hi:[0,1]
	v_pk_fma_f32 v[50:51], v[50:51], v[174:175], v[136:137] op_sel:[0,1,0] op_sel_hi:[1,1,1] neg_lo:[0,0,1]
	v_pk_mul_f32 v[52:53], v[52:53], s[36:37] op_sel_hi:[1,0]
	v_pk_mul_f32 v[54:55], v[54:55], s[36:37] op_sel_hi:[1,0]
	v_pk_mul_f32 v[48:49], v[48:49], s[36:37] op_sel_hi:[1,0]
	v_pk_mul_f32 v[50:51], v[50:51], s[36:37] op_sel_hi:[1,0]
	v_cvt_pk_bf16_f32 v144, v52, v53
	v_cvt_pk_bf16_f32 v145, v54, v55
	v_cvt_pk_bf16_f32 v146, v48, v49
	v_cvt_pk_bf16_f32 v147, v50, v51
	global_store_dwordx4 v130, v[144:147], s[6:7] offset:64
	s_add_u32 s6, s6, s33
	s_addc_u32 s7, s7, 0
	s_add_u32 s8, s8, 0x800
	s_addc_u32 s9, s9, 0
	global_load_dwordx4 v[164:167], v131, s[8:9]
	global_load_dwordx4 v[168:171], v132, s[8:9]
	global_load_dwordx4 v[172:175], v131, s[8:9] offset:64
	global_load_dwordx4 v[176:179], v132, s[8:9] offset:64
	s_waitcnt vmcnt(6)
	v_pk_mul_f32 v[136:137], v[44:45], v[206:207] op_sel:[1,0] op_sel_hi:[0,0]
	v_pk_fma_f32 v[44:45], v[44:45], v[202:203], v[136:137] op_sel:[0,0,0] op_sel_hi:[1,0,1] neg_lo:[0,0,1]
	v_pk_mul_f32 v[136:137], v[46:47], v[206:207] op_sel:[1,1] op_sel_hi:[0,1]
	v_pk_fma_f32 v[46:47], v[46:47], v[202:203], v[136:137] op_sel:[0,1,0] op_sel_hi:[1,1,1] neg_lo:[0,0,1]
	v_pk_mul_f32 v[136:137], v[40:41], v[208:209] op_sel:[1,0] op_sel_hi:[0,0]
	v_pk_fma_f32 v[40:41], v[40:41], v[204:205], v[136:137] op_sel:[0,0,0] op_sel_hi:[1,0,1] neg_lo:[0,0,1]
	v_pk_mul_f32 v[136:137], v[42:43], v[208:209] op_sel:[1,1] op_sel_hi:[0,1]
	v_pk_fma_f32 v[42:43], v[42:43], v[204:205], v[136:137] op_sel:[0,1,0] op_sel_hi:[1,1,1] neg_lo:[0,0,1]
	v_pk_mul_f32 v[44:45], v[44:45], s[36:37] op_sel_hi:[1,0]
	v_pk_mul_f32 v[46:47], v[46:47], s[36:37] op_sel_hi:[1,0]
	v_pk_mul_f32 v[40:41], v[40:41], s[36:37] op_sel_hi:[1,0]
	v_pk_mul_f32 v[42:43], v[42:43], s[36:37] op_sel_hi:[1,0]
	v_cvt_pk_bf16_f32 v140, v44, v45
	v_cvt_pk_bf16_f32 v141, v46, v47
	v_cvt_pk_bf16_f32 v142, v40, v41
	v_cvt_pk_bf16_f32 v143, v42, v43
	global_store_dwordx4 v130, v[140:143], s[6:7]
	v_pk_mul_f32 v[136:137], v[36:37], v[214:215] op_sel:[1,0] op_sel_hi:[0,0]
	v_pk_fma_f32 v[36:37], v[36:37], v[210:211], v[136:137] op_sel:[0,0,0] op_sel_hi:[1,0,1] neg_lo:[0,0,1]
	v_pk_mul_f32 v[136:137], v[38:39], v[214:215] op_sel:[1,1] op_sel_hi:[0,1]
	v_pk_fma_f32 v[38:39], v[38:39], v[210:211], v[136:137] op_sel:[0,1,0] op_sel_hi:[1,1,1] neg_lo:[0,0,1]
	v_pk_mul_f32 v[136:137], v[32:33], v[216:217] op_sel:[1,0] op_sel_hi:[0,0]
	v_pk_fma_f32 v[32:33], v[32:33], v[212:213], v[136:137] op_sel:[0,0,0] op_sel_hi:[1,0,1] neg_lo:[0,0,1]
	v_pk_mul_f32 v[136:137], v[34:35], v[216:217] op_sel:[1,1] op_sel_hi:[0,1]
	v_pk_fma_f32 v[34:35], v[34:35], v[212:213], v[136:137] op_sel:[0,1,0] op_sel_hi:[1,1,1] neg_lo:[0,0,1]
	v_pk_mul_f32 v[36:37], v[36:37], s[36:37] op_sel_hi:[1,0]
	v_pk_mul_f32 v[38:39], v[38:39], s[36:37] op_sel_hi:[1,0]
	v_pk_mul_f32 v[32:33], v[32:33], s[36:37] op_sel_hi:[1,0]
	v_pk_mul_f32 v[34:35], v[34:35], s[36:37] op_sel_hi:[1,0]
	v_cvt_pk_bf16_f32 v144, v36, v37
	v_cvt_pk_bf16_f32 v145, v38, v39
	v_cvt_pk_bf16_f32 v146, v32, v33
	v_cvt_pk_bf16_f32 v147, v34, v35
	global_store_dwordx4 v130, v[144:147], s[6:7] offset:64
	s_add_u32 s6, s6, s33
	s_addc_u32 s7, s7, 0
	s_add_u32 s8, s8, 0x800
	s_addc_u32 s9, s9, 0
	global_load_dwordx4 v[202:205], v131, s[8:9]
	global_load_dwordx4 v[206:209], v132, s[8:9]
	global_load_dwordx4 v[210:213], v131, s[8:9] offset:64
	global_load_dwordx4 v[214:217], v132, s[8:9] offset:64
	s_waitcnt vmcnt(6)
	v_pk_mul_f32 v[136:137], v[28:29], v[168:169] op_sel:[1,0] op_sel_hi:[0,0]
	v_pk_fma_f32 v[28:29], v[28:29], v[164:165], v[136:137] op_sel:[0,0,0] op_sel_hi:[1,0,1] neg_lo:[0,0,1]
	v_pk_mul_f32 v[136:137], v[30:31], v[168:169] op_sel:[1,1] op_sel_hi:[0,1]
	v_pk_fma_f32 v[30:31], v[30:31], v[164:165], v[136:137] op_sel:[0,1,0] op_sel_hi:[1,1,1] neg_lo:[0,0,1]
	v_pk_mul_f32 v[136:137], v[24:25], v[170:171] op_sel:[1,0] op_sel_hi:[0,0]
	v_pk_fma_f32 v[24:25], v[24:25], v[166:167], v[136:137] op_sel:[0,0,0] op_sel_hi:[1,0,1] neg_lo:[0,0,1]
	v_pk_mul_f32 v[136:137], v[26:27], v[170:171] op_sel:[1,1] op_sel_hi:[0,1]
	v_pk_fma_f32 v[26:27], v[26:27], v[166:167], v[136:137] op_sel:[0,1,0] op_sel_hi:[1,1,1] neg_lo:[0,0,1]
	v_pk_mul_f32 v[28:29], v[28:29], s[36:37] op_sel_hi:[1,0]
	v_pk_mul_f32 v[30:31], v[30:31], s[36:37] op_sel_hi:[1,0]
	v_pk_mul_f32 v[24:25], v[24:25], s[36:37] op_sel_hi:[1,0]
	v_pk_mul_f32 v[26:27], v[26:27], s[36:37] op_sel_hi:[1,0]
	v_cvt_pk_bf16_f32 v140, v28, v29
	v_cvt_pk_bf16_f32 v141, v30, v31
	v_cvt_pk_bf16_f32 v142, v24, v25
	v_cvt_pk_bf16_f32 v143, v26, v27
	global_store_dwordx4 v130, v[140:143], s[6:7]
	v_pk_mul_f32 v[136:137], v[20:21], v[176:177] op_sel:[1,0] op_sel_hi:[0,0]
	v_pk_fma_f32 v[20:21], v[20:21], v[172:173], v[136:137] op_sel:[0,0,0] op_sel_hi:[1,0,1] neg_lo:[0,0,1]
	v_pk_mul_f32 v[136:137], v[22:23], v[176:177] op_sel:[1,1] op_sel_hi:[0,1]
	v_pk_fma_f32 v[22:23], v[22:23], v[172:173], v[136:137] op_sel:[0,1,0] op_sel_hi:[1,1,1] neg_lo:[0,0,1]
	v_pk_mul_f32 v[136:137], v[16:17], v[178:179] op_sel:[1,0] op_sel_hi:[0,0]
	v_pk_fma_f32 v[16:17], v[16:17], v[174:175], v[136:137] op_sel:[0,0,0] op_sel_hi:[1,0,1] neg_lo:[0,0,1]
	v_pk_mul_f32 v[136:137], v[18:19], v[178:179] op_sel:[1,1] op_sel_hi:[0,1]
	v_pk_fma_f32 v[18:19], v[18:19], v[174:175], v[136:137] op_sel:[0,1,0] op_sel_hi:[1,1,1] neg_lo:[0,0,1]
	v_pk_mul_f32 v[20:21], v[20:21], s[36:37] op_sel_hi:[1,0]
	v_pk_mul_f32 v[22:23], v[22:23], s[36:37] op_sel_hi:[1,0]
	v_pk_mul_f32 v[16:17], v[16:17], s[36:37] op_sel_hi:[1,0]
	v_pk_mul_f32 v[18:19], v[18:19], s[36:37] op_sel_hi:[1,0]
	v_cvt_pk_bf16_f32 v144, v20, v21
	v_cvt_pk_bf16_f32 v145, v22, v23
	v_cvt_pk_bf16_f32 v146, v16, v17
	v_cvt_pk_bf16_f32 v147, v18, v19
	global_store_dwordx4 v130, v[144:147], s[6:7] offset:64
	s_add_u32 s6, s6, s33
	s_addc_u32 s7, s7, 0
	s_waitcnt vmcnt(2)
	v_pk_mul_f32 v[136:137], v[12:13], v[206:207] op_sel:[1,0] op_sel_hi:[0,0]
	v_pk_fma_f32 v[12:13], v[12:13], v[202:203], v[136:137] op_sel:[0,0,0] op_sel_hi:[1,0,1] neg_lo:[0,0,1]
	v_pk_mul_f32 v[136:137], v[14:15], v[206:207] op_sel:[1,1] op_sel_hi:[0,1]
	v_pk_fma_f32 v[14:15], v[14:15], v[202:203], v[136:137] op_sel:[0,1,0] op_sel_hi:[1,1,1] neg_lo:[0,0,1]
	v_pk_mul_f32 v[136:137], v[4:5], v[208:209] op_sel:[1,0] op_sel_hi:[0,0]
	v_pk_fma_f32 v[4:5], v[4:5], v[204:205], v[136:137] op_sel:[0,0,0] op_sel_hi:[1,0,1] neg_lo:[0,0,1]
	v_pk_mul_f32 v[136:137], v[6:7], v[208:209] op_sel:[1,1] op_sel_hi:[0,1]
	v_pk_fma_f32 v[6:7], v[6:7], v[204:205], v[136:137] op_sel:[0,1,0] op_sel_hi:[1,1,1] neg_lo:[0,0,1]
	v_pk_mul_f32 v[12:13], v[12:13], s[36:37] op_sel_hi:[1,0]
	v_pk_mul_f32 v[14:15], v[14:15], s[36:37] op_sel_hi:[1,0]
	v_pk_mul_f32 v[4:5], v[4:5], s[36:37] op_sel_hi:[1,0]
	v_pk_mul_f32 v[6:7], v[6:7], s[36:37] op_sel_hi:[1,0]
	v_cvt_pk_bf16_f32 v140, v12, v13
	v_cvt_pk_bf16_f32 v141, v14, v15
	v_cvt_pk_bf16_f32 v142, v4, v5
	v_cvt_pk_bf16_f32 v143, v6, v7
	global_store_dwordx4 v130, v[140:143], s[6:7]
	v_pk_mul_f32 v[136:137], v[8:9], v[214:215] op_sel:[1,0] op_sel_hi:[0,0]
	v_pk_fma_f32 v[8:9], v[8:9], v[210:211], v[136:137] op_sel:[0,0,0] op_sel_hi:[1,0,1] neg_lo:[0,0,1]
	v_pk_mul_f32 v[136:137], v[10:11], v[214:215] op_sel:[1,1] op_sel_hi:[0,1]
	v_pk_fma_f32 v[10:11], v[10:11], v[210:211], v[136:137] op_sel:[0,1,0] op_sel_hi:[1,1,1] neg_lo:[0,0,1]
	v_pk_mul_f32 v[136:137], v[0:1], v[216:217] op_sel:[1,0] op_sel_hi:[0,0]
	v_pk_fma_f32 v[0:1], v[0:1], v[212:213], v[136:137] op_sel:[0,0,0] op_sel_hi:[1,0,1] neg_lo:[0,0,1]
	v_pk_mul_f32 v[136:137], v[2:3], v[216:217] op_sel:[1,1] op_sel_hi:[0,1]
	v_pk_fma_f32 v[2:3], v[2:3], v[212:213], v[136:137] op_sel:[0,1,0] op_sel_hi:[1,1,1] neg_lo:[0,0,1]
	v_pk_mul_f32 v[8:9], v[8:9], s[36:37] op_sel_hi:[1,0]
	v_pk_mul_f32 v[10:11], v[10:11], s[36:37] op_sel_hi:[1,0]
	v_pk_mul_f32 v[0:1], v[0:1], s[36:37] op_sel_hi:[1,0]
	v_pk_mul_f32 v[2:3], v[2:3], s[36:37] op_sel_hi:[1,0]
	v_cvt_pk_bf16_f32 v144, v8, v9
	v_cvt_pk_bf16_f32 v145, v10, v11
	v_cvt_pk_bf16_f32 v146, v0, v1
	v_cvt_pk_bf16_f32 v147, v2, v3
	global_store_dwordx4 v130, v[144:147], s[6:7] offset:64
	s_branch .LBB0_638
.Lq3_D:
	v_pk_mul_f32 v[126:127], v[126:127], s[36:37] op_sel_hi:[1,0]
	v_pk_mul_f32 v[128:129], v[128:129], s[36:37] op_sel_hi:[1,0]
	v_pk_mul_f32 v[122:123], v[122:123], s[36:37] op_sel_hi:[1,0]
	v_pk_mul_f32 v[124:125], v[124:125], s[36:37] op_sel_hi:[1,0]
	v_cvt_pk_bf16_f32 v140, v126, v127
	v_cvt_pk_bf16_f32 v141, v128, v129
	v_cvt_pk_bf16_f32 v142, v122, v123
	v_cvt_pk_bf16_f32 v143, v124, v125
	global_store_dwordx4 v130, v[140:143], s[6:7]
	v_pk_mul_f32 v[118:119], v[118:119], s[36:37] op_sel_hi:[1,0]
	v_pk_mul_f32 v[120:121], v[120:121], s[36:37] op_sel_hi:[1,0]
	v_pk_mul_f32 v[114:115], v[114:115], s[36:37] op_sel_hi:[1,0]
	v_pk_mul_f32 v[116:117], v[116:117], s[36:37] op_sel_hi:[1,0]
	v_cvt_pk_bf16_f32 v144, v118, v119
	v_cvt_pk_bf16_f32 v145, v120, v121
	v_cvt_pk_bf16_f32 v146, v114, v115
	v_cvt_pk_bf16_f32 v147, v116, v117
	global_store_dwordx4 v130, v[144:147], s[6:7] offset:64
	s_add_u32 s6, s6, s33
	s_addc_u32 s7, s7, 0
	v_pk_mul_f32 v[108:109], v[108:109], s[36:37] op_sel_hi:[1,0]
	v_pk_mul_f32 v[110:111], v[110:111], s[36:37] op_sel_hi:[1,0]
	v_pk_mul_f32 v[104:105], v[104:105], s[36:37] op_sel_hi:[1,0]
	v_pk_mul_f32 v[106:107], v[106:107], s[36:37] op_sel_hi:[1,0]
	v_cvt_pk_bf16_f32 v140, v108, v109
	v_cvt_pk_bf16_f32 v141, v110, v111
	v_cvt_pk_bf16_f32 v142, v104, v105
	v_cvt_pk_bf16_f32 v143, v106, v107
	global_store_dwordx4 v130, v[140:143], s[6:7]
	v_pk_mul_f32 v[100:101], v[100:101], s[36:37] op_sel_hi:[1,0]
	v_pk_mul_f32 v[102:103], v[102:103], s[36:37] op_sel_hi:[1,0]
	v_pk_mul_f32 v[96:97], v[96:97], s[36:37] op_sel_hi:[1,0]
	v_pk_mul_f32 v[98:99], v[98:99], s[36:37] op_sel_hi:[1,0]
	v_cvt_pk_bf16_f32 v144, v100, v101
	v_cvt_pk_bf16_f32 v145, v102, v103
	v_cvt_pk_bf16_f32 v146, v96, v97
	v_cvt_pk_bf16_f32 v147, v98, v99
	global_store_dwordx4 v130, v[144:147], s[6:7] offset:64
	s_add_u32 s6, s6, s33
	s_addc_u32 s7, s7, 0
	v_pk_mul_f32 v[92:93], v[92:93], s[36:37] op_sel_hi:[1,0]
	v_pk_mul_f32 v[94:95], v[94:95], s[36:37] op_sel_hi:[1,0]
	v_pk_mul_f32 v[88:89], v[88:89], s[36:37] op_sel_hi:[1,0]
	v_pk_mul_f32 v[90:91], v[90:91], s[36:37] op_sel_hi:[1,0]
	v_cvt_pk_bf16_f32 v140, v92, v93
	v_cvt_pk_bf16_f32 v141, v94, v95
	v_cvt_pk_bf16_f32 v142, v88, v89
	v_cvt_pk_bf16_f32 v143, v90, v91
	global_store_dwordx4 v130, v[140:143], s[6:7]
	v_pk_mul_f32 v[84:85], v[84:85], s[36:37] op_sel_hi:[1,0]
	v_pk_mul_f32 v[86:87], v[86:87], s[36:37] op_sel_hi:[1,0]
	v_pk_mul_f32 v[80:81], v[80:81], s[36:37] op_sel_hi:[1,0]
	v_pk_mul_f32 v[82:83], v[82:83], s[36:37] op_sel_hi:[1,0]
	v_cvt_pk_bf16_f32 v144, v84, v85
	v_cvt_pk_bf16_f32 v145, v86, v87
	v_cvt_pk_bf16_f32 v146, v80, v81
	v_cvt_pk_bf16_f32 v147, v82, v83
	global_store_dwordx4 v130, v[144:147], s[6:7] offset:64
	s_add_u32 s6, s6, s33
	s_addc_u32 s7, s7, 0
	v_pk_mul_f32 v[76:77], v[76:77], s[36:37] op_sel_hi:[1,0]
	v_pk_mul_f32 v[78:79], v[78:79], s[36:37] op_sel_hi:[1,0]
	v_pk_mul_f32 v[72:73], v[72:73], s[36:37] op_sel_hi:[1,0]
	v_pk_mul_f32 v[74:75], v[74:75], s[36:37] op_sel_hi:[1,0]
	v_cvt_pk_bf16_f32 v140, v76, v77
	v_cvt_pk_bf16_f32 v141, v78, v79
	v_cvt_pk_bf16_f32 v142, v72, v73
	v_cvt_pk_bf16_f32 v143, v74, v75
	global_store_dwordx4 v130, v[140:143], s[6:7]
	v_pk_mul_f32 v[68:69], v[68:69], s[36:37] op_sel_hi:[1,0]
	v_pk_mul_f32 v[70:71], v[70:71], s[36:37] op_sel_hi:[1,0]
	v_pk_mul_f32 v[64:65], v[64:65], s[36:37] op_sel_hi:[1,0]
	v_pk_mul_f32 v[66:67], v[66:67], s[36:37] op_sel_hi:[1,0]
	v_cvt_pk_bf16_f32 v144, v68, v69
	v_cvt_pk_bf16_f32 v145, v70, v71
	v_cvt_pk_bf16_f32 v146, v64, v65
	v_cvt_pk_bf16_f32 v147, v66, v67
	global_store_dwordx4 v130, v[144:147], s[6:7] offset:64
	s_add_u32 s6, s6, s34
	s_addc_u32 s7, s7, 0
	v_pk_mul_f32 v[60:61], v[60:61], s[36:37] op_sel_hi:[1,0]
	v_pk_mul_f32 v[62:63], v[62:63], s[36:37] op_sel_hi:[1,0]
	v_pk_mul_f32 v[56:57], v[56:57], s[36:37] op_sel_hi:[1,0]
	v_pk_mul_f32 v[58:59], v[58:59], s[36:37] op_sel_hi:[1,0]
	v_cvt_pk_bf16_f32 v140, v60, v61
	v_cvt_pk_bf16_f32 v141, v62, v63
	v_cvt_pk_bf16_f32 v142, v56, v57
	v_cvt_pk_bf16_f32 v143, v58, v59
	global_store_dwordx4 v130, v[140:143], s[6:7]
	v_pk_mul_f32 v[52:53], v[52:53], s[36:37] op_sel_hi:[1,0]
	v_pk_mul_f32 v[54:55], v[54:55], s[36:37] op_sel_hi:[1,0]
	v_pk_mul_f32 v[48:49], v[48:49], s[36:37] op_sel_hi:[1,0]
	v_pk_mul_f32 v[50:51], v[50:51], s[36:37] op_sel_hi:[1,0]
	v_cvt_pk_bf16_f32 v144, v52, v53
	v_cvt_pk_bf16_f32 v145, v54, v55
	v_cvt_pk_bf16_f32 v146, v48, v49
	v_cvt_pk_bf16_f32 v147, v50, v51
	global_store_dwordx4 v130, v[144:147], s[6:7] offset:64
	s_add_u32 s6, s6, s33
	s_addc_u32 s7, s7, 0
	v_pk_mul_f32 v[44:45], v[44:45], s[36:37] op_sel_hi:[1,0]
	v_pk_mul_f32 v[46:47], v[46:47], s[36:37] op_sel_hi:[1,0]
	v_pk_mul_f32 v[40:41], v[40:41], s[36:37] op_sel_hi:[1,0]
	v_pk_mul_f32 v[42:43], v[42:43], s[36:37] op_sel_hi:[1,0]
	v_cvt_pk_bf16_f32 v140, v44, v45
	v_cvt_pk_bf16_f32 v141, v46, v47
	v_cvt_pk_bf16_f32 v142, v40, v41
	v_cvt_pk_bf16_f32 v143, v42, v43
	global_store_dwordx4 v130, v[140:143], s[6:7]
	v_pk_mul_f32 v[36:37], v[36:37], s[36:37] op_sel_hi:[1,0]
	v_pk_mul_f32 v[38:39], v[38:39], s[36:37] op_sel_hi:[1,0]
	v_pk_mul_f32 v[32:33], v[32:33], s[36:37] op_sel_hi:[1,0]
	v_pk_mul_f32 v[34:35], v[34:35], s[36:37] op_sel_hi:[1,0]
	v_cvt_pk_bf16_f32 v144, v36, v37
	v_cvt_pk_bf16_f32 v145, v38, v39
	v_cvt_pk_bf16_f32 v146, v32, v33
	v_cvt_pk_bf16_f32 v147, v34, v35
	global_store_dwordx4 v130, v[144:147], s[6:7] offset:64
	s_add_u32 s6, s6, s33
	s_addc_u32 s7, s7, 0
	v_pk_mul_f32 v[28:29], v[28:29], s[36:37] op_sel_hi:[1,0]
	v_pk_mul_f32 v[30:31], v[30:31], s[36:37] op_sel_hi:[1,0]
	v_pk_mul_f32 v[24:25], v[24:25], s[36:37] op_sel_hi:[1,0]
	v_pk_mul_f32 v[26:27], v[26:27], s[36:37] op_sel_hi:[1,0]
	v_cvt_pk_bf16_f32 v140, v28, v29
	v_cvt_pk_bf16_f32 v141, v30, v31
	v_cvt_pk_bf16_f32 v142, v24, v25
	v_cvt_pk_bf16_f32 v143, v26, v27
	global_store_dwordx4 v130, v[140:143], s[6:7]
	v_pk_mul_f32 v[20:21], v[20:21], s[36:37] op_sel_hi:[1,0]
	v_pk_mul_f32 v[22:23], v[22:23], s[36:37] op_sel_hi:[1,0]
	v_pk_mul_f32 v[16:17], v[16:17], s[36:37] op_sel_hi:[1,0]
	v_pk_mul_f32 v[18:19], v[18:19], s[36:37] op_sel_hi:[1,0]
	v_cvt_pk_bf16_f32 v144, v20, v21
	v_cvt_pk_bf16_f32 v145, v22, v23
	v_cvt_pk_bf16_f32 v146, v16, v17
	v_cvt_pk_bf16_f32 v147, v18, v19
	global_store_dwordx4 v130, v[144:147], s[6:7] offset:64
	s_add_u32 s6, s6, s33
	s_addc_u32 s7, s7, 0
	v_pk_mul_f32 v[12:13], v[12:13], s[36:37] op_sel_hi:[1,0]
	v_pk_mul_f32 v[14:15], v[14:15], s[36:37] op_sel_hi:[1,0]
	v_pk_mul_f32 v[4:5], v[4:5], s[36:37] op_sel_hi:[1,0]
	v_pk_mul_f32 v[6:7], v[6:7], s[36:37] op_sel_hi:[1,0]
	v_cvt_pk_bf16_f32 v140, v12, v13
	v_cvt_pk_bf16_f32 v141, v14, v15
	v_cvt_pk_bf16_f32 v142, v4, v5
	v_cvt_pk_bf16_f32 v143, v6, v7
	global_store_dwordx4 v130, v[140:143], s[6:7]
	v_pk_mul_f32 v[8:9], v[8:9], s[36:37] op_sel_hi:[1,0]
	v_pk_mul_f32 v[10:11], v[10:11], s[36:37] op_sel_hi:[1,0]
	v_pk_mul_f32 v[0:1], v[0:1], s[36:37] op_sel_hi:[1,0]
	v_pk_mul_f32 v[2:3], v[2:3], s[36:37] op_sel_hi:[1,0]
	v_cvt_pk_bf16_f32 v144, v8, v9
	v_cvt_pk_bf16_f32 v145, v10, v11
	v_cvt_pk_bf16_f32 v146, v0, v1
	v_cvt_pk_bf16_f32 v147, v2, v3
	global_store_dwordx4 v130, v[144:147], s[6:7] offset:64
	s_branch .LBB0_638
.LBB0_448:
	s_mov_b32 s68, 2
	s_movk_i32 s14, 0x100
	s_cbranch_execz .LBB0_282
	s_branch .LBB0_283
.LBB0_638:
	s_mov_b64 s[4:5], 0
